# QKV epilogue rewritten by hand (gains/rope tables up front, batched bpermute, no store waits) + Up epilogue canonicalize removal
# speedup vs baseline: 1.0538x; 1.0145x over previous
;     __device__ __forceinline__ void operator()(const f32x4 (&acc)[2][2][4][2], const pg8::Unit& u, int wr, int wc, int fr, int fq) const {
;         const int pn = u.pn; const int kind = pn < 4 ? 0 : (pn < 4 + nk_tiles ? 1 : 2);
;         const int hd = (kind == 0 ? pn : (kind == 1 ? pn - 4 : pn - 4 - nk_tiles)) * 4 + wc;
;         bf16_t* dst = Q + (size_t)kind * kstride + hd * 64 + 8 * fq; const int pitch = kind == 0 ? DM : kvpitch;
;         const float* gp = gains + (kind & 1) * 64 + 8 * fq;
;         const bool dorope = (rope != nullptr) && kind < 2 && u.pm < 128;
;         const float* rp = rope + 8 * (fq & 1);
;         int rbase = u.pm * 256 + wr * 64 + fr; asm volatile("" : "+v"(rbase));
;         const int paddr = ((fr + 16 * fq) ^ 32) << 2;
; #pragma unroll
;         for (int ai = 0; ai < 2; ++ai)
; #pragma unroll
;             for (int m = 0; m < 4; ++m) {
;                 const int row = rbase + ai * 128 + m * 16;
;                 float rs = 1.0f;
;                 if (kind < 2) {
;                     float ss = 0.f;
; #pragma unroll
;                     for (int bj = 0; bj < 2; ++bj)
; #pragma unroll
;                         for (int n = 0; n < 2; ++n) { const f32x4 x = acc[ai][bj][m][n]; ss += (x[0] * x[0] + x[1] * x[1]) + (x[2] * x[2] + x[3] * x[3]); }
;                     ss = xsum4(ss);
;                     rs = rsqrtf(ss * (1.0f / 64.0f) + EPS);
;                 }
;                 const int t = row & (SEQ - 1);
; #pragma unroll
;                 for (int bj = 0; bj < 2; ++bj) {
;                     f32x4 v0 = acc[ai][bj][m][0], v1 = acc[ai][bj][m][1];
;                     if (kind < 2) {
;                         v0 = v0 * rs * *(const f32x4*)(gp + 32 * bj); v1 = v1 * rs * *(const f32x4*)(gp + 32 * bj + 4);
;                         if (dorope) {
;                             const int pos = bj ? (t & 63) : (t >> 6);
;                             const f32x4 c0 = *(const f32x4*)(rp + pos * 16), c1 = *(const f32x4*)(rp + pos * 16 + 4);
;                             const f32x4 s0 = *(const f32x4*)(rp + 2048 + pos * 16), s1 = *(const f32x4*)(rp + 2048 + pos * 16 + 4);
;                             f32x4 o0, o1;
; #pragma unroll
.LBB0_220:
	s_sub_i32 s10, s28, s62
	s_add_i32 s11, s28, -4
	s_cmp_lt_i32 s28, s62
	s_cselect_b32 s10, s11, s10
	s_cselect_b32 s11, 1, 2
	s_cselect_b64 s[34:35], -1, 0
	s_cmp_lt_i32 s28, 4
	s_cselect_b32 s10, s28, s10
	s_cselect_b32 s11, 0, s11
	s_cselect_b64 s[30:31], -1, 0
	v_readlane_b32 s36, v241, 37
	v_readlane_b32 s37, v241, 38
	v_readlane_b32 s38, v240, 36
	v_readlane_b32 s39, v240, 38
	s_mul_i32 s13, s11, 0x4200000
	s_lshl_b32 s10, s10, 8
	s_or_b32 s10, s10, s57
	s_lshl_b32 s10, s10, 1
	s_add_u32 s36, s36, s13
	s_addc_u32 s37, s37, 0
	s_add_u32 s36, s36, s10
	s_addc_u32 s37, s37, 0
	s_cmp_lg_u32 s38, 0
	s_cselect_b32 s13, 11, 9
	s_cmp_lt_i32 s28, 4
	s_cselect_b32 s13, 11, s13
	s_cmp_eq_u32 s11, 1
	s_cselect_b32 s82, 0x100, 0
	s_cmp_lt_i32 s12, 0x80
	s_cselect_b32 s38, s39, 0
	s_cmp_lt_i32 s11, 2
	s_cselect_b32 s38, s38, 0
	s_cmp_eq_u32 s11, 2
	s_cbranch_scc1 .Lqkv_v
	s_cmp_lg_u32 s38, 0
	s_cbranch_scc1 .Lqkv_rope
	v_lshl_add_u64 v[214:215], v[136:137], 0, s[82:83]
	global_load_dwordx4 v[162:165], v[214:215], off
	global_load_dwordx4 v[166:169], v[214:215], off offset:16
	global_load_dwordx4 v[170:173], v[214:215], off offset:128
	global_load_dwordx4 v[174:177], v[214:215], off offset:144
	v_mul_f32_e32 v143, v125, v125
	v_mul_f32_e32 v144, v127, v127
	v_fmac_f32_e32 v143, v124, v124
	v_fmac_f32_e32 v144, v126, v126
	v_add_f32_e32 v142, v143, v144
	v_mul_f32_e32 v143, v121, v121
	v_mul_f32_e32 v144, v123, v123
	v_fmac_f32_e32 v143, v120, v120
	v_fmac_f32_e32 v144, v122, v122
	v_add_f32_e32 v143, v143, v144
	v_add_f32_e32 v142, v142, v143
	v_mul_f32_e32 v143, v117, v117
	v_mul_f32_e32 v144, v119, v119
	v_fmac_f32_e32 v143, v116, v116
	v_fmac_f32_e32 v144, v118, v118
	v_add_f32_e32 v143, v143, v144
	v_add_f32_e32 v142, v142, v143
	v_mul_f32_e32 v143, v113, v113
	v_mul_f32_e32 v144, v115, v115
	v_fmac_f32_e32 v143, v112, v112
	v_fmac_f32_e32 v144, v114, v114
	v_add_f32_e32 v143, v143, v144
	v_add_f32_e32 v142, v142, v143
	v_mov_b32_e32 v143, v142
	s_nop 1
	v_permlane16_swap_b32_e32 v142, v143
	v_add_f32_e32 v142, v142, v143
	v_mov_b32_e32 v143, v142
	s_nop 1
	v_permlane32_swap_b32_e32 v142, v143
	v_add_f32_e32 v142, v142, v143
	v_fmamk_f32 v144, v142, 0x3c800000, v153
	v_rsq_f32_e32 v144, v144
	s_nop 0
	s_waitcnt vmcnt(0)
	v_pk_mul_f32 v[124:125], v[124:125], v[144:145] op_sel_hi:[1,0]
	v_pk_mul_f32 v[126:127], v[126:127], v[144:145] op_sel_hi:[1,0]
	v_pk_mul_f32 v[124:125], v[124:125], v[162:163]
	v_pk_mul_f32 v[126:127], v[126:127], v[164:165]
	v_pk_mul_f32 v[120:121], v[120:121], v[144:145] op_sel_hi:[1,0]
	v_pk_mul_f32 v[122:123], v[122:123], v[144:145] op_sel_hi:[1,0]
	v_pk_mul_f32 v[120:121], v[120:121], v[166:167]
	v_pk_mul_f32 v[122:123], v[122:123], v[168:169]
	v_pk_mul_f32 v[116:117], v[116:117], v[144:145] op_sel_hi:[1,0]
	v_pk_mul_f32 v[118:119], v[118:119], v[144:145] op_sel_hi:[1,0]
	v_pk_mul_f32 v[116:117], v[116:117], v[170:171]
	v_pk_mul_f32 v[118:119], v[118:119], v[172:173]
	v_pk_mul_f32 v[112:113], v[112:113], v[144:145] op_sel_hi:[1,0]
	v_pk_mul_f32 v[114:115], v[114:115], v[144:145] op_sel_hi:[1,0]
	v_pk_mul_f32 v[112:113], v[112:113], v[174:175]
	v_pk_mul_f32 v[114:115], v[114:115], v[176:177]
	v_lshl_add_u32 v142, s12, 8, v158
	v_lshl_add_u32 v142, v142, s13, v154
	v_cvt_pk_bf16_f32 v124, v124, v125
	v_cvt_pk_bf16_f32 v125, v126, v127
	v_cvt_pk_bf16_f32 v126, v120, v121
	v_cvt_pk_bf16_f32 v127, v122, v123
	global_store_dwordx4 v142, v[124:127], s[36:37]
	v_cvt_pk_bf16_f32 v116, v116, v117
	v_cvt_pk_bf16_f32 v117, v118, v119
	v_cvt_pk_bf16_f32 v118, v112, v113
	v_cvt_pk_bf16_f32 v119, v114, v115
	global_store_dwordx4 v142, v[116:119], s[36:37] offset:64
	v_mul_f32_e32 v143, v109, v109
	v_mul_f32_e32 v144, v111, v111
	v_fmac_f32_e32 v143, v108, v108
	v_fmac_f32_e32 v144, v110, v110
	v_add_f32_e32 v142, v143, v144
	v_mul_f32_e32 v143, v105, v105
	v_mul_f32_e32 v144, v107, v107
	v_fmac_f32_e32 v143, v104, v104
	v_fmac_f32_e32 v144, v106, v106
	v_add_f32_e32 v143, v143, v144
	v_add_f32_e32 v142, v142, v143
	v_mul_f32_e32 v143, v101, v101
	v_mul_f32_e32 v144, v103, v103
	v_fmac_f32_e32 v143, v100, v100
	v_fmac_f32_e32 v144, v102, v102
	v_add_f32_e32 v143, v143, v144
	v_add_f32_e32 v142, v142, v143
	v_mul_f32_e32 v143, v97, v97
	v_mul_f32_e32 v144, v99, v99
	v_fmac_f32_e32 v143, v96, v96
	v_fmac_f32_e32 v144, v98, v98
	v_add_f32_e32 v143, v143, v144
	v_add_f32_e32 v142, v142, v143
	v_mov_b32_e32 v143, v142
	s_nop 1
	v_permlane16_swap_b32_e32 v142, v143
	v_add_f32_e32 v142, v142, v143
	v_mov_b32_e32 v143, v142
	s_nop 1
	v_permlane32_swap_b32_e32 v142, v143
	v_add_f32_e32 v142, v142, v143
	v_fmamk_f32 v144, v142, 0x3c800000, v153
	v_rsq_f32_e32 v144, v144
	s_nop 0
	v_pk_mul_f32 v[108:109], v[108:109], v[144:145] op_sel_hi:[1,0]
	v_pk_mul_f32 v[110:111], v[110:111], v[144:145] op_sel_hi:[1,0]
	v_pk_mul_f32 v[108:109], v[108:109], v[162:163]
	v_pk_mul_f32 v[110:111], v[110:111], v[164:165]
	v_pk_mul_f32 v[104:105], v[104:105], v[144:145] op_sel_hi:[1,0]
	v_pk_mul_f32 v[106:107], v[106:107], v[144:145] op_sel_hi:[1,0]
	v_pk_mul_f32 v[104:105], v[104:105], v[166:167]
	v_pk_mul_f32 v[106:107], v[106:107], v[168:169]
	v_pk_mul_f32 v[100:101], v[100:101], v[144:145] op_sel_hi:[1,0]
	v_pk_mul_f32 v[102:103], v[102:103], v[144:145] op_sel_hi:[1,0]
	v_pk_mul_f32 v[100:101], v[100:101], v[170:171]
	v_pk_mul_f32 v[102:103], v[102:103], v[172:173]
	v_pk_mul_f32 v[96:97], v[96:97], v[144:145] op_sel_hi:[1,0]
	v_pk_mul_f32 v[98:99], v[98:99], v[144:145] op_sel_hi:[1,0]
	v_pk_mul_f32 v[96:97], v[96:97], v[174:175]
	v_pk_mul_f32 v[98:99], v[98:99], v[176:177]
	v_lshl_add_u32 v142, s12, 8, v158
	v_add_u32_e32 v142, 16, v142
;     __device__ __forceinline__ void operator()(const f32x4 (&acc)[2][2][4][2], const pg8::Unit& u, int wr, int wc, int fr, int fq) const {
;     ...
;         for (int ai = 0; ai < 2; ++ai)
; #pragma unroll
;             for (int m = 0; m < 4; ++m) {
;                 const int row = rbase + ai * 128 + m * 16;
;                 float rs = 1.0f;
;                 if (kind < 2) {
;                     float ss = 0.f;
; #pragma unroll
;                     for (int bj = 0; bj < 2; ++bj)
; #pragma unroll
;                         for (int n = 0; n < 2; ++n) { const f32x4 x = acc[ai][bj][m][n]; ss += (x[0] * x[0] + x[1] * x[1]) + (x[2] * x[2] + x[3] * x[3]); }
;                     ss = xsum4(ss);
;                     rs = rsqrtf(ss * (1.0f / 64.0f) + EPS);
;                 }
;                 const int t = row & (SEQ - 1);
; #pragma unroll
;                 for (int bj = 0; bj < 2; ++bj) {
;                     f32x4 v0 = acc[ai][bj][m][0], v1 = acc[ai][bj][m][1];
;                     if (kind < 2) {
;                         v0 = v0 * rs * *(const f32x4*)(gp + 32 * bj); v1 = v1 * rs * *(const f32x4*)(gp + 32 * bj + 4);
;                         if (dorope) {
;                             const int pos = bj ? (t & 63) : (t >> 6);
;                             const f32x4 c0 = *(const f32x4*)(rp + pos * 16), c1 = *(const f32x4*)(rp + pos * 16 + 4);
;                             const f32x4 s0 = *(const f32x4*)(rp + 2048 + pos * 16), s1 = *(const f32x4*)(rp + 2048 + pos * 16 + 4);
;                             f32x4 o0, o1;
; #pragma unroll
;                             for (int i = 0; i < 4; ++i) { const float p0 = __uint_as_float((unsigned)__builtin_amdgcn_ds_bpermute(paddr, (int)__float_as_uint(v0[i]))) * s0[i], p1 = __uint_as_float((unsigned)__builtin_amdgcn_ds_bpermute(paddr, (int)__float_as_uint(v1[i]))) * s1[i];
;                                 o0[i] = v0[i] * c0[i] + (fq >= 2 ? p0 : -p0); o1[i] = v1[i] * c1[i] + (fq >= 2 ? p1 : -p1); }
;                             v0 = o0; v1 = o1;
;                         }
;                     }
;                     u32x4 w; w.x = pkbf(v0[0], v0[1]); w.y = pkbf(v0[2], v0[3]); w.z = pkbf(v1[0], v1[1]); w.w = pkbf(v1[2], v1[3]);
;                     *(u32x4*)(dst + (size_t)row * pitch + 32 * bj) = w;
	v_lshl_add_u32 v142, v142, s13, v154
	v_cvt_pk_bf16_f32 v108, v108, v109
	v_cvt_pk_bf16_f32 v109, v110, v111
	v_cvt_pk_bf16_f32 v110, v104, v105
	v_cvt_pk_bf16_f32 v111, v106, v107
	global_store_dwordx4 v142, v[108:111], s[36:37]
	v_cvt_pk_bf16_f32 v100, v100, v101
	v_cvt_pk_bf16_f32 v101, v102, v103
	v_cvt_pk_bf16_f32 v102, v96, v97
	v_cvt_pk_bf16_f32 v103, v98, v99
	global_store_dwordx4 v142, v[100:103], s[36:37] offset:64
	v_mul_f32_e32 v143, v93, v93
	v_mul_f32_e32 v144, v95, v95
	v_fmac_f32_e32 v143, v92, v92
	v_fmac_f32_e32 v144, v94, v94
	v_add_f32_e32 v142, v143, v144
	v_mul_f32_e32 v143, v89, v89
	v_mul_f32_e32 v144, v91, v91
	v_fmac_f32_e32 v143, v88, v88
	v_fmac_f32_e32 v144, v90, v90
	v_add_f32_e32 v143, v143, v144
	v_add_f32_e32 v142, v142, v143
	v_mul_f32_e32 v143, v85, v85
	v_mul_f32_e32 v144, v87, v87
	v_fmac_f32_e32 v143, v84, v84
	v_fmac_f32_e32 v144, v86, v86
	v_add_f32_e32 v143, v143, v144
	v_add_f32_e32 v142, v142, v143
	v_mul_f32_e32 v143, v81, v81
	v_mul_f32_e32 v144, v83, v83
	v_fmac_f32_e32 v143, v80, v80
	v_fmac_f32_e32 v144, v82, v82
	v_add_f32_e32 v143, v143, v144
	v_add_f32_e32 v142, v142, v143
	v_mov_b32_e32 v143, v142
	s_nop 1
	v_permlane16_swap_b32_e32 v142, v143
	v_add_f32_e32 v142, v142, v143
	v_mov_b32_e32 v143, v142
	s_nop 1
	v_permlane32_swap_b32_e32 v142, v143
	v_add_f32_e32 v142, v142, v143
	v_fmamk_f32 v144, v142, 0x3c800000, v153
	v_rsq_f32_e32 v144, v144
	s_nop 0
	v_pk_mul_f32 v[92:93], v[92:93], v[144:145] op_sel_hi:[1,0]
	v_pk_mul_f32 v[94:95], v[94:95], v[144:145] op_sel_hi:[1,0]
	v_pk_mul_f32 v[92:93], v[92:93], v[162:163]
	v_pk_mul_f32 v[94:95], v[94:95], v[164:165]
	v_pk_mul_f32 v[88:89], v[88:89], v[144:145] op_sel_hi:[1,0]
	v_pk_mul_f32 v[90:91], v[90:91], v[144:145] op_sel_hi:[1,0]
	v_pk_mul_f32 v[88:89], v[88:89], v[166:167]
	v_pk_mul_f32 v[90:91], v[90:91], v[168:169]
	v_pk_mul_f32 v[84:85], v[84:85], v[144:145] op_sel_hi:[1,0]
	v_pk_mul_f32 v[86:87], v[86:87], v[144:145] op_sel_hi:[1,0]
	v_pk_mul_f32 v[84:85], v[84:85], v[170:171]
	v_pk_mul_f32 v[86:87], v[86:87], v[172:173]
	v_pk_mul_f32 v[80:81], v[80:81], v[144:145] op_sel_hi:[1,0]
	v_pk_mul_f32 v[82:83], v[82:83], v[144:145] op_sel_hi:[1,0]
	v_pk_mul_f32 v[80:81], v[80:81], v[174:175]
	v_pk_mul_f32 v[82:83], v[82:83], v[176:177]
	v_lshl_add_u32 v142, s12, 8, v158
	v_add_u32_e32 v142, 32, v142
	v_lshl_add_u32 v142, v142, s13, v154
	v_cvt_pk_bf16_f32 v92, v92, v93
	v_cvt_pk_bf16_f32 v93, v94, v95
	v_cvt_pk_bf16_f32 v94, v88, v89
	v_cvt_pk_bf16_f32 v95, v90, v91
	global_store_dwordx4 v142, v[92:95], s[36:37]
	v_cvt_pk_bf16_f32 v84, v84, v85
	v_cvt_pk_bf16_f32 v85, v86, v87
	v_cvt_pk_bf16_f32 v86, v80, v81
	v_cvt_pk_bf16_f32 v87, v82, v83
	global_store_dwordx4 v142, v[84:87], s[36:37] offset:64
	v_mul_f32_e32 v143, v77, v77
	v_mul_f32_e32 v144, v79, v79
	v_fmac_f32_e32 v143, v76, v76
	v_fmac_f32_e32 v144, v78, v78
	v_add_f32_e32 v142, v143, v144
	v_mul_f32_e32 v143, v73, v73
	v_mul_f32_e32 v144, v75, v75
	v_fmac_f32_e32 v143, v72, v72
	v_fmac_f32_e32 v144, v74, v74
	v_add_f32_e32 v143, v143, v144
	v_add_f32_e32 v142, v142, v143
	v_mul_f32_e32 v143, v69, v69
	v_mul_f32_e32 v144, v71, v71
	v_fmac_f32_e32 v143, v68, v68
	v_fmac_f32_e32 v144, v70, v70
	v_add_f32_e32 v143, v143, v144
	v_add_f32_e32 v142, v142, v143
	v_mul_f32_e32 v143, v65, v65
	v_mul_f32_e32 v144, v67, v67
	v_fmac_f32_e32 v143, v64, v64
	v_fmac_f32_e32 v144, v66, v66
	v_add_f32_e32 v143, v143, v144
	v_add_f32_e32 v142, v142, v143
	v_mov_b32_e32 v143, v142
	s_nop 1
	v_permlane16_swap_b32_e32 v142, v143
	v_add_f32_e32 v142, v142, v143
	v_mov_b32_e32 v143, v142
	s_nop 1
	v_permlane32_swap_b32_e32 v142, v143
	v_add_f32_e32 v142, v142, v143
	v_fmamk_f32 v144, v142, 0x3c800000, v153
	v_rsq_f32_e32 v144, v144
	s_nop 0
	v_pk_mul_f32 v[76:77], v[76:77], v[144:145] op_sel_hi:[1,0]
	v_pk_mul_f32 v[78:79], v[78:79], v[144:145] op_sel_hi:[1,0]
	v_pk_mul_f32 v[76:77], v[76:77], v[162:163]
	v_pk_mul_f32 v[78:79], v[78:79], v[164:165]
	v_pk_mul_f32 v[72:73], v[72:73], v[144:145] op_sel_hi:[1,0]
	v_pk_mul_f32 v[74:75], v[74:75], v[144:145] op_sel_hi:[1,0]
	v_pk_mul_f32 v[72:73], v[72:73], v[166:167]
	v_pk_mul_f32 v[74:75], v[74:75], v[168:169]
	v_pk_mul_f32 v[68:69], v[68:69], v[144:145] op_sel_hi:[1,0]
	v_pk_mul_f32 v[70:71], v[70:71], v[144:145] op_sel_hi:[1,0]
	v_pk_mul_f32 v[68:69], v[68:69], v[170:171]
	v_pk_mul_f32 v[70:71], v[70:71], v[172:173]
	v_pk_mul_f32 v[64:65], v[64:65], v[144:145] op_sel_hi:[1,0]
	v_pk_mul_f32 v[66:67], v[66:67], v[144:145] op_sel_hi:[1,0]
	v_pk_mul_f32 v[64:65], v[64:65], v[174:175]
	v_pk_mul_f32 v[66:67], v[66:67], v[176:177]
	v_lshl_add_u32 v142, s12, 8, v158
	v_add_u32_e32 v142, 48, v142
	v_lshl_add_u32 v142, v142, s13, v154
	v_cvt_pk_bf16_f32 v76, v76, v77
	v_cvt_pk_bf16_f32 v77, v78, v79
	v_cvt_pk_bf16_f32 v78, v72, v73
	v_cvt_pk_bf16_f32 v79, v74, v75
	global_store_dwordx4 v142, v[76:79], s[36:37]
	v_cvt_pk_bf16_f32 v68, v68, v69
	v_cvt_pk_bf16_f32 v69, v70, v71
	v_cvt_pk_bf16_f32 v70, v64, v65
	v_cvt_pk_bf16_f32 v71, v66, v67
	global_store_dwordx4 v142, v[68:71], s[36:37] offset:64
	v_mul_f32_e32 v143, v61, v61
	v_mul_f32_e32 v144, v63, v63
	v_fmac_f32_e32 v143, v60, v60
	v_fmac_f32_e32 v144, v62, v62
	v_add_f32_e32 v142, v143, v144
	v_mul_f32_e32 v143, v57, v57
	v_mul_f32_e32 v144, v59, v59
	v_fmac_f32_e32 v143, v56, v56
	v_fmac_f32_e32 v144, v58, v58
	v_add_f32_e32 v143, v143, v144
	v_add_f32_e32 v142, v142, v143
	v_mul_f32_e32 v143, v53, v53
	v_mul_f32_e32 v144, v55, v55
	v_fmac_f32_e32 v143, v52, v52
	v_fmac_f32_e32 v144, v54, v54
	v_add_f32_e32 v143, v143, v144
	v_add_f32_e32 v142, v142, v143
	v_mul_f32_e32 v143, v49, v49
	v_mul_f32_e32 v144, v51, v51
;     __device__ __forceinline__ void operator()(const f32x4 (&acc)[2][2][4][2], const pg8::Unit& u, int wr, int wc, int fr, int fq) const {
;     ...
;         for (int ai = 0; ai < 2; ++ai)
; #pragma unroll
;             for (int m = 0; m < 4; ++m) {
;                 const int row = rbase + ai * 128 + m * 16;
;                 float rs = 1.0f;
;                 if (kind < 2) {
;                     float ss = 0.f;
; #pragma unroll
;                     for (int bj = 0; bj < 2; ++bj)
; #pragma unroll
;                         for (int n = 0; n < 2; ++n) { const f32x4 x = acc[ai][bj][m][n]; ss += (x[0] * x[0] + x[1] * x[1]) + (x[2] * x[2] + x[3] * x[3]); }
;                     ss = xsum4(ss);
;                     rs = rsqrtf(ss * (1.0f / 64.0f) + EPS);
;                 }
;                 const int t = row & (SEQ - 1);
; #pragma unroll
;                 for (int bj = 0; bj < 2; ++bj) {
;                     f32x4 v0 = acc[ai][bj][m][0], v1 = acc[ai][bj][m][1];
;                     if (kind < 2) {
;                         v0 = v0 * rs * *(const f32x4*)(gp + 32 * bj); v1 = v1 * rs * *(const f32x4*)(gp + 32 * bj + 4);
;                         if (dorope) {
;                             const int pos = bj ? (t & 63) : (t >> 6);
;                             const f32x4 c0 = *(const f32x4*)(rp + pos * 16), c1 = *(const f32x4*)(rp + pos * 16 + 4);
;                             const f32x4 s0 = *(const f32x4*)(rp + 2048 + pos * 16), s1 = *(const f32x4*)(rp + 2048 + pos * 16 + 4);
;                             f32x4 o0, o1;
; #pragma unroll
;                             for (int i = 0; i < 4; ++i) { const float p0 = __uint_as_float((unsigned)__builtin_amdgcn_ds_bpermute(paddr, (int)__float_as_uint(v0[i]))) * s0[i], p1 = __uint_as_float((unsigned)__builtin_amdgcn_ds_bpermute(paddr, (int)__float_as_uint(v1[i]))) * s1[i];
;                                 o0[i] = v0[i] * c0[i] + (fq >= 2 ? p0 : -p0); o1[i] = v1[i] * c1[i] + (fq >= 2 ? p1 : -p1); }
;                             v0 = o0; v1 = o1;
;                         }
;                     }
;                     u32x4 w; w.x = pkbf(v0[0], v0[1]); w.y = pkbf(v0[2], v0[3]); w.z = pkbf(v1[0], v1[1]); w.w = pkbf(v1[2], v1[3]);
;                     *(u32x4*)(dst + (size_t)row * pitch + 32 * bj) = w;
	v_fmac_f32_e32 v143, v48, v48
	v_fmac_f32_e32 v144, v50, v50
	v_add_f32_e32 v143, v143, v144
	v_add_f32_e32 v142, v142, v143
	v_mov_b32_e32 v143, v142
	s_nop 1
	v_permlane16_swap_b32_e32 v142, v143
	v_add_f32_e32 v142, v142, v143
	v_mov_b32_e32 v143, v142
	s_nop 1
	v_permlane32_swap_b32_e32 v142, v143
	v_add_f32_e32 v142, v142, v143
	v_fmamk_f32 v144, v142, 0x3c800000, v153
	v_rsq_f32_e32 v144, v144
	s_nop 0
	v_pk_mul_f32 v[60:61], v[60:61], v[144:145] op_sel_hi:[1,0]
	v_pk_mul_f32 v[62:63], v[62:63], v[144:145] op_sel_hi:[1,0]
	v_pk_mul_f32 v[60:61], v[60:61], v[162:163]
	v_pk_mul_f32 v[62:63], v[62:63], v[164:165]
	v_pk_mul_f32 v[56:57], v[56:57], v[144:145] op_sel_hi:[1,0]
	v_pk_mul_f32 v[58:59], v[58:59], v[144:145] op_sel_hi:[1,0]
	v_pk_mul_f32 v[56:57], v[56:57], v[166:167]
	v_pk_mul_f32 v[58:59], v[58:59], v[168:169]
	v_pk_mul_f32 v[52:53], v[52:53], v[144:145] op_sel_hi:[1,0]
	v_pk_mul_f32 v[54:55], v[54:55], v[144:145] op_sel_hi:[1,0]
	v_pk_mul_f32 v[52:53], v[52:53], v[170:171]
	v_pk_mul_f32 v[54:55], v[54:55], v[172:173]
	v_pk_mul_f32 v[48:49], v[48:49], v[144:145] op_sel_hi:[1,0]
	v_pk_mul_f32 v[50:51], v[50:51], v[144:145] op_sel_hi:[1,0]
	v_pk_mul_f32 v[48:49], v[48:49], v[174:175]
	v_pk_mul_f32 v[50:51], v[50:51], v[176:177]
	v_lshl_add_u32 v142, s12, 8, v158
	v_add_u32_e32 v142, 128, v142
	v_lshl_add_u32 v142, v142, s13, v154
	v_cvt_pk_bf16_f32 v60, v60, v61
	v_cvt_pk_bf16_f32 v61, v62, v63
	v_cvt_pk_bf16_f32 v62, v56, v57
	v_cvt_pk_bf16_f32 v63, v58, v59
	global_store_dwordx4 v142, v[60:63], s[36:37]
	v_cvt_pk_bf16_f32 v52, v52, v53
	v_cvt_pk_bf16_f32 v53, v54, v55
	v_cvt_pk_bf16_f32 v54, v48, v49
	v_cvt_pk_bf16_f32 v55, v50, v51
	global_store_dwordx4 v142, v[52:55], s[36:37] offset:64
	v_mul_f32_e32 v143, v45, v45
	v_mul_f32_e32 v144, v47, v47
	v_fmac_f32_e32 v143, v44, v44
	v_fmac_f32_e32 v144, v46, v46
	v_add_f32_e32 v142, v143, v144
	v_mul_f32_e32 v143, v41, v41
	v_mul_f32_e32 v144, v43, v43
	v_fmac_f32_e32 v143, v40, v40
	v_fmac_f32_e32 v144, v42, v42
	v_add_f32_e32 v143, v143, v144
	v_add_f32_e32 v142, v142, v143
	v_mul_f32_e32 v143, v37, v37
	v_mul_f32_e32 v144, v39, v39
	v_fmac_f32_e32 v143, v36, v36
	v_fmac_f32_e32 v144, v38, v38
	v_add_f32_e32 v143, v143, v144
	v_add_f32_e32 v142, v142, v143
	v_mul_f32_e32 v143, v33, v33
	v_mul_f32_e32 v144, v35, v35
	v_fmac_f32_e32 v143, v32, v32
	v_fmac_f32_e32 v144, v34, v34
	v_add_f32_e32 v143, v143, v144
	v_add_f32_e32 v142, v142, v143
	v_mov_b32_e32 v143, v142
	s_nop 1
	v_permlane16_swap_b32_e32 v142, v143
	v_add_f32_e32 v142, v142, v143
	v_mov_b32_e32 v143, v142
	s_nop 1
	v_permlane32_swap_b32_e32 v142, v143
	v_add_f32_e32 v142, v142, v143
	v_fmamk_f32 v144, v142, 0x3c800000, v153
	v_rsq_f32_e32 v144, v144
	s_nop 0
	v_pk_mul_f32 v[44:45], v[44:45], v[144:145] op_sel_hi:[1,0]
	v_pk_mul_f32 v[46:47], v[46:47], v[144:145] op_sel_hi:[1,0]
	v_pk_mul_f32 v[44:45], v[44:45], v[162:163]
	v_pk_mul_f32 v[46:47], v[46:47], v[164:165]
	v_pk_mul_f32 v[40:41], v[40:41], v[144:145] op_sel_hi:[1,0]
	v_pk_mul_f32 v[42:43], v[42:43], v[144:145] op_sel_hi:[1,0]
	v_pk_mul_f32 v[40:41], v[40:41], v[166:167]
	v_pk_mul_f32 v[42:43], v[42:43], v[168:169]
	v_pk_mul_f32 v[36:37], v[36:37], v[144:145] op_sel_hi:[1,0]
	v_pk_mul_f32 v[38:39], v[38:39], v[144:145] op_sel_hi:[1,0]
	v_pk_mul_f32 v[36:37], v[36:37], v[170:171]
	v_pk_mul_f32 v[38:39], v[38:39], v[172:173]
	v_pk_mul_f32 v[32:33], v[32:33], v[144:145] op_sel_hi:[1,0]
	v_pk_mul_f32 v[34:35], v[34:35], v[144:145] op_sel_hi:[1,0]
	v_pk_mul_f32 v[32:33], v[32:33], v[174:175]
	v_pk_mul_f32 v[34:35], v[34:35], v[176:177]
	v_lshl_add_u32 v142, s12, 8, v158
	v_add_u32_e32 v142, 144, v142
	v_lshl_add_u32 v142, v142, s13, v154
	v_cvt_pk_bf16_f32 v44, v44, v45
	v_cvt_pk_bf16_f32 v45, v46, v47
	v_cvt_pk_bf16_f32 v46, v40, v41
	v_cvt_pk_bf16_f32 v47, v42, v43
	global_store_dwordx4 v142, v[44:47], s[36:37]
	v_cvt_pk_bf16_f32 v36, v36, v37
	v_cvt_pk_bf16_f32 v37, v38, v39
	v_cvt_pk_bf16_f32 v38, v32, v33
	v_cvt_pk_bf16_f32 v39, v34, v35
	global_store_dwordx4 v142, v[36:39], s[36:37] offset:64
	v_mul_f32_e32 v143, v29, v29
	v_mul_f32_e32 v144, v31, v31
	v_fmac_f32_e32 v143, v28, v28
	v_fmac_f32_e32 v144, v30, v30
	v_add_f32_e32 v142, v143, v144
	v_mul_f32_e32 v143, v25, v25
	v_mul_f32_e32 v144, v27, v27
	v_fmac_f32_e32 v143, v24, v24
	v_fmac_f32_e32 v144, v26, v26
	v_add_f32_e32 v143, v143, v144
	v_add_f32_e32 v142, v142, v143
	v_mul_f32_e32 v143, v21, v21
	v_mul_f32_e32 v144, v23, v23
	v_fmac_f32_e32 v143, v20, v20
	v_fmac_f32_e32 v144, v22, v22
	v_add_f32_e32 v143, v143, v144
	v_add_f32_e32 v142, v142, v143
	v_mul_f32_e32 v143, v17, v17
	v_mul_f32_e32 v144, v19, v19
	v_fmac_f32_e32 v143, v16, v16
	v_fmac_f32_e32 v144, v18, v18
	v_add_f32_e32 v143, v143, v144
	v_add_f32_e32 v142, v142, v143
	v_mov_b32_e32 v143, v142
	s_nop 1
	v_permlane16_swap_b32_e32 v142, v143
	v_add_f32_e32 v142, v142, v143
	v_mov_b32_e32 v143, v142
	s_nop 1
	v_permlane32_swap_b32_e32 v142, v143
	v_add_f32_e32 v142, v142, v143
	v_fmamk_f32 v144, v142, 0x3c800000, v153
	v_rsq_f32_e32 v144, v144
	s_nop 0
	v_pk_mul_f32 v[28:29], v[28:29], v[144:145] op_sel_hi:[1,0]
	v_pk_mul_f32 v[30:31], v[30:31], v[144:145] op_sel_hi:[1,0]
	v_pk_mul_f32 v[28:29], v[28:29], v[162:163]
	v_pk_mul_f32 v[30:31], v[30:31], v[164:165]
	v_pk_mul_f32 v[24:25], v[24:25], v[144:145] op_sel_hi:[1,0]
	v_pk_mul_f32 v[26:27], v[26:27], v[144:145] op_sel_hi:[1,0]
	v_pk_mul_f32 v[24:25], v[24:25], v[166:167]
	v_pk_mul_f32 v[26:27], v[26:27], v[168:169]
	v_pk_mul_f32 v[20:21], v[20:21], v[144:145] op_sel_hi:[1,0]
	v_pk_mul_f32 v[22:23], v[22:23], v[144:145] op_sel_hi:[1,0]
	v_pk_mul_f32 v[20:21], v[20:21], v[170:171]
;     __device__ __forceinline__ void operator()(const f32x4 (&acc)[2][2][4][2], const pg8::Unit& u, int wr, int wc, int fr, int fq) const {
;     ...
;         for (int ai = 0; ai < 2; ++ai)
; #pragma unroll
;             for (int m = 0; m < 4; ++m) {
;                 const int row = rbase + ai * 128 + m * 16;
;                 float rs = 1.0f;
;                 if (kind < 2) {
;                     float ss = 0.f;
; #pragma unroll
;                     for (int bj = 0; bj < 2; ++bj)
; #pragma unroll
;                         for (int n = 0; n < 2; ++n) { const f32x4 x = acc[ai][bj][m][n]; ss += (x[0] * x[0] + x[1] * x[1]) + (x[2] * x[2] + x[3] * x[3]); }
;                     ss = xsum4(ss);
;                     rs = rsqrtf(ss * (1.0f / 64.0f) + EPS);
;                 }
;                 const int t = row & (SEQ - 1);
; #pragma unroll
;                 for (int bj = 0; bj < 2; ++bj) {
;                     f32x4 v0 = acc[ai][bj][m][0], v1 = acc[ai][bj][m][1];
;                     if (kind < 2) {
;                         v0 = v0 * rs * *(const f32x4*)(gp + 32 * bj); v1 = v1 * rs * *(const f32x4*)(gp + 32 * bj + 4);
;                         if (dorope) {
;                             const int pos = bj ? (t & 63) : (t >> 6);
;                             const f32x4 c0 = *(const f32x4*)(rp + pos * 16), c1 = *(const f32x4*)(rp + pos * 16 + 4);
;                             const f32x4 s0 = *(const f32x4*)(rp + 2048 + pos * 16), s1 = *(const f32x4*)(rp + 2048 + pos * 16 + 4);
;                             f32x4 o0, o1;
; #pragma unroll
;                             for (int i = 0; i < 4; ++i) { const float p0 = __uint_as_float((unsigned)__builtin_amdgcn_ds_bpermute(paddr, (int)__float_as_uint(v0[i]))) * s0[i], p1 = __uint_as_float((unsigned)__builtin_amdgcn_ds_bpermute(paddr, (int)__float_as_uint(v1[i]))) * s1[i];
;                                 o0[i] = v0[i] * c0[i] + (fq >= 2 ? p0 : -p0); o1[i] = v1[i] * c1[i] + (fq >= 2 ? p1 : -p1); }
;                             v0 = o0; v1 = o1;
;                         }
;                     }
;                     u32x4 w; w.x = pkbf(v0[0], v0[1]); w.y = pkbf(v0[2], v0[3]); w.z = pkbf(v1[0], v1[1]); w.w = pkbf(v1[2], v1[3]);
;                     *(u32x4*)(dst + (size_t)row * pitch + 32 * bj) = w;
	v_pk_mul_f32 v[22:23], v[22:23], v[172:173]
	v_pk_mul_f32 v[16:17], v[16:17], v[144:145] op_sel_hi:[1,0]
	v_pk_mul_f32 v[18:19], v[18:19], v[144:145] op_sel_hi:[1,0]
	v_pk_mul_f32 v[16:17], v[16:17], v[174:175]
	v_pk_mul_f32 v[18:19], v[18:19], v[176:177]
	v_lshl_add_u32 v142, s12, 8, v158
	v_add_u32_e32 v142, 160, v142
	v_lshl_add_u32 v142, v142, s13, v154
	v_cvt_pk_bf16_f32 v28, v28, v29
	v_cvt_pk_bf16_f32 v29, v30, v31
	v_cvt_pk_bf16_f32 v30, v24, v25
	v_cvt_pk_bf16_f32 v31, v26, v27
	global_store_dwordx4 v142, v[28:31], s[36:37]
	v_cvt_pk_bf16_f32 v20, v20, v21
	v_cvt_pk_bf16_f32 v21, v22, v23
	v_cvt_pk_bf16_f32 v22, v16, v17
	v_cvt_pk_bf16_f32 v23, v18, v19
	global_store_dwordx4 v142, v[20:23], s[36:37] offset:64
	v_mul_f32_e32 v143, v13, v13
	v_mul_f32_e32 v144, v15, v15
	v_fmac_f32_e32 v143, v12, v12
	v_fmac_f32_e32 v144, v14, v14
	v_add_f32_e32 v142, v143, v144
	v_mul_f32_e32 v143, v9, v9
	v_mul_f32_e32 v144, v11, v11
	v_fmac_f32_e32 v143, v8, v8
	v_fmac_f32_e32 v144, v10, v10
	v_add_f32_e32 v143, v143, v144
	v_add_f32_e32 v142, v142, v143
	v_mul_f32_e32 v143, v5, v5
	v_mul_f32_e32 v144, v7, v7
	v_fmac_f32_e32 v143, v4, v4
	v_fmac_f32_e32 v144, v6, v6
	v_add_f32_e32 v143, v143, v144
	v_add_f32_e32 v142, v142, v143
	v_mul_f32_e32 v143, v1, v1
	v_mul_f32_e32 v144, v3, v3
	v_fmac_f32_e32 v143, v0, v0
	v_fmac_f32_e32 v144, v2, v2
	v_add_f32_e32 v143, v143, v144
	v_add_f32_e32 v142, v142, v143
	v_mov_b32_e32 v143, v142
	s_nop 1
	v_permlane16_swap_b32_e32 v142, v143
	v_add_f32_e32 v142, v142, v143
	v_mov_b32_e32 v143, v142
	s_nop 1
	v_permlane32_swap_b32_e32 v142, v143
	v_add_f32_e32 v142, v142, v143
	v_fmamk_f32 v144, v142, 0x3c800000, v153
	v_rsq_f32_e32 v144, v144
	s_nop 0
	v_pk_mul_f32 v[12:13], v[12:13], v[144:145] op_sel_hi:[1,0]
	v_pk_mul_f32 v[14:15], v[14:15], v[144:145] op_sel_hi:[1,0]
	v_pk_mul_f32 v[12:13], v[12:13], v[162:163]
	v_pk_mul_f32 v[14:15], v[14:15], v[164:165]
	v_pk_mul_f32 v[8:9], v[8:9], v[144:145] op_sel_hi:[1,0]
	v_pk_mul_f32 v[10:11], v[10:11], v[144:145] op_sel_hi:[1,0]
	v_pk_mul_f32 v[8:9], v[8:9], v[166:167]
	v_pk_mul_f32 v[10:11], v[10:11], v[168:169]
	v_pk_mul_f32 v[4:5], v[4:5], v[144:145] op_sel_hi:[1,0]
	v_pk_mul_f32 v[6:7], v[6:7], v[144:145] op_sel_hi:[1,0]
	v_pk_mul_f32 v[4:5], v[4:5], v[170:171]
	v_pk_mul_f32 v[6:7], v[6:7], v[172:173]
	v_pk_mul_f32 v[0:1], v[0:1], v[144:145] op_sel_hi:[1,0]
	v_pk_mul_f32 v[2:3], v[2:3], v[144:145] op_sel_hi:[1,0]
	v_pk_mul_f32 v[0:1], v[0:1], v[174:175]
	v_pk_mul_f32 v[2:3], v[2:3], v[176:177]
	v_lshl_add_u32 v142, s12, 8, v158
	v_add_u32_e32 v142, 176, v142
	v_lshl_add_u32 v142, v142, s13, v154
	v_cvt_pk_bf16_f32 v12, v12, v13
	v_cvt_pk_bf16_f32 v13, v14, v15
	v_cvt_pk_bf16_f32 v14, v8, v9
	v_cvt_pk_bf16_f32 v15, v10, v11
	global_store_dwordx4 v142, v[12:15], s[36:37]
	v_cvt_pk_bf16_f32 v4, v4, v5
	v_cvt_pk_bf16_f32 v5, v6, v7
	v_cvt_pk_bf16_f32 v6, v0, v1
	v_cvt_pk_bf16_f32 v7, v2, v3
	global_store_dwordx4 v142, v[4:7], s[36:37] offset:64
	s_branch .Lqkv_join
.Lqkv_v:
	v_lshl_add_u32 v142, s12, 8, v158
	v_lshl_add_u32 v142, v142, s13, v154
	v_cvt_pk_bf16_f32 v124, v124, v125
	v_cvt_pk_bf16_f32 v125, v126, v127
	v_cvt_pk_bf16_f32 v126, v120, v121
	v_cvt_pk_bf16_f32 v127, v122, v123
	global_store_dwordx4 v142, v[124:127], s[36:37]
	v_cvt_pk_bf16_f32 v116, v116, v117
	v_cvt_pk_bf16_f32 v117, v118, v119
	v_cvt_pk_bf16_f32 v118, v112, v113
	v_cvt_pk_bf16_f32 v119, v114, v115
	global_store_dwordx4 v142, v[116:119], s[36:37] offset:64
	v_lshl_add_u32 v142, s12, 8, v158
	v_add_u32_e32 v142, 16, v142
	v_lshl_add_u32 v142, v142, s13, v154
	v_cvt_pk_bf16_f32 v108, v108, v109
	v_cvt_pk_bf16_f32 v109, v110, v111
	v_cvt_pk_bf16_f32 v110, v104, v105
	v_cvt_pk_bf16_f32 v111, v106, v107
	global_store_dwordx4 v142, v[108:111], s[36:37]
	v_cvt_pk_bf16_f32 v100, v100, v101
	v_cvt_pk_bf16_f32 v101, v102, v103
	v_cvt_pk_bf16_f32 v102, v96, v97
	v_cvt_pk_bf16_f32 v103, v98, v99
	global_store_dwordx4 v142, v[100:103], s[36:37] offset:64
	v_lshl_add_u32 v142, s12, 8, v158
	v_add_u32_e32 v142, 32, v142
	v_lshl_add_u32 v142, v142, s13, v154
	v_cvt_pk_bf16_f32 v92, v92, v93
	v_cvt_pk_bf16_f32 v93, v94, v95
	v_cvt_pk_bf16_f32 v94, v88, v89
	v_cvt_pk_bf16_f32 v95, v90, v91
	global_store_dwordx4 v142, v[92:95], s[36:37]
	v_cvt_pk_bf16_f32 v84, v84, v85
	v_cvt_pk_bf16_f32 v85, v86, v87
	v_cvt_pk_bf16_f32 v86, v80, v81
	v_cvt_pk_bf16_f32 v87, v82, v83
	global_store_dwordx4 v142, v[84:87], s[36:37] offset:64
	v_lshl_add_u32 v142, s12, 8, v158
	v_add_u32_e32 v142, 48, v142
	v_lshl_add_u32 v142, v142, s13, v154
	v_cvt_pk_bf16_f32 v76, v76, v77
	v_cvt_pk_bf16_f32 v77, v78, v79
	v_cvt_pk_bf16_f32 v78, v72, v73
	v_cvt_pk_bf16_f32 v79, v74, v75
	global_store_dwordx4 v142, v[76:79], s[36:37]
	v_cvt_pk_bf16_f32 v68, v68, v69
	v_cvt_pk_bf16_f32 v69, v70, v71
	v_cvt_pk_bf16_f32 v70, v64, v65
	v_cvt_pk_bf16_f32 v71, v66, v67
	global_store_dwordx4 v142, v[68:71], s[36:37] offset:64
	v_lshl_add_u32 v142, s12, 8, v158
	v_add_u32_e32 v142, 128, v142
	v_lshl_add_u32 v142, v142, s13, v154
	v_cvt_pk_bf16_f32 v60, v60, v61
	v_cvt_pk_bf16_f32 v61, v62, v63
	v_cvt_pk_bf16_f32 v62, v56, v57
	v_cvt_pk_bf16_f32 v63, v58, v59
	global_store_dwordx4 v142, v[60:63], s[36:37]
	v_cvt_pk_bf16_f32 v52, v52, v53
	v_cvt_pk_bf16_f32 v53, v54, v55
	v_cvt_pk_bf16_f32 v54, v48, v49
	v_cvt_pk_bf16_f32 v55, v50, v51
	global_store_dwordx4 v142, v[52:55], s[36:37] offset:64
	v_lshl_add_u32 v142, s12, 8, v158
	v_add_u32_e32 v142, 144, v142
	v_lshl_add_u32 v142, v142, s13, v154
	v_cvt_pk_bf16_f32 v44, v44, v45
	v_cvt_pk_bf16_f32 v45, v46, v47
	v_cvt_pk_bf16_f32 v46, v40, v41
	v_cvt_pk_bf16_f32 v47, v42, v43
	global_store_dwordx4 v142, v[44:47], s[36:37]
	v_cvt_pk_bf16_f32 v36, v36, v37
	v_cvt_pk_bf16_f32 v37, v38, v39
	v_cvt_pk_bf16_f32 v38, v32, v33
	v_cvt_pk_bf16_f32 v39, v34, v35
	global_store_dwordx4 v142, v[36:39], s[36:37] offset:64
	v_lshl_add_u32 v142, s12, 8, v158
	v_add_u32_e32 v142, 160, v142
	v_lshl_add_u32 v142, v142, s13, v154
	v_cvt_pk_bf16_f32 v28, v28, v29
	v_cvt_pk_bf16_f32 v29, v30, v31
	v_cvt_pk_bf16_f32 v30, v24, v25
	v_cvt_pk_bf16_f32 v31, v26, v27
	global_store_dwordx4 v142, v[28:31], s[36:37]
	v_cvt_pk_bf16_f32 v20, v20, v21
	v_cvt_pk_bf16_f32 v21, v22, v23
	v_cvt_pk_bf16_f32 v22, v16, v17
	v_cvt_pk_bf16_f32 v23, v18, v19
	global_store_dwordx4 v142, v[20:23], s[36:37] offset:64
	v_lshl_add_u32 v142, s12, 8, v158
	v_add_u32_e32 v142, 176, v142
	v_lshl_add_u32 v142, v142, s13, v154
	v_cvt_pk_bf16_f32 v12, v12, v13
	v_cvt_pk_bf16_f32 v13, v14, v15
	v_cvt_pk_bf16_f32 v14, v8, v9
	v_cvt_pk_bf16_f32 v15, v10, v11
	global_store_dwordx4 v142, v[12:15], s[36:37]
	v_cvt_pk_bf16_f32 v4, v4, v5
	v_cvt_pk_bf16_f32 v5, v6, v7
	v_cvt_pk_bf16_f32 v6, v0, v1
	v_cvt_pk_bf16_f32 v7, v2, v3
	global_store_dwordx4 v142, v[4:7], s[36:37] offset:64
	s_branch .Lqkv_join
;     __device__ __forceinline__ void operator()(const f32x4 (&acc)[2][2][4][2], const pg8::Unit& u, int wr, int wc, int fr, int fq) const {
;     ...
;         for (int ai = 0; ai < 2; ++ai)
; #pragma unroll
;             for (int m = 0; m < 4; ++m) {
;                 const int row = rbase + ai * 128 + m * 16;
;                 float rs = 1.0f;
;                 if (kind < 2) {
;                     float ss = 0.f;
; #pragma unroll
;                     for (int bj = 0; bj < 2; ++bj)
; #pragma unroll
;                         for (int n = 0; n < 2; ++n) { const f32x4 x = acc[ai][bj][m][n]; ss += (x[0] * x[0] + x[1] * x[1]) + (x[2] * x[2] + x[3] * x[3]); }
;                     ss = xsum4(ss);
;                     rs = rsqrtf(ss * (1.0f / 64.0f) + EPS);
;                 }
;                 const int t = row & (SEQ - 1);
; #pragma unroll
;                 for (int bj = 0; bj < 2; ++bj) {
;                     f32x4 v0 = acc[ai][bj][m][0], v1 = acc[ai][bj][m][1];
;                     if (kind < 2) {
;                         v0 = v0 * rs * *(const f32x4*)(gp + 32 * bj); v1 = v1 * rs * *(const f32x4*)(gp + 32 * bj + 4);
;                         if (dorope) {
;                             const int pos = bj ? (t & 63) : (t >> 6);
;                             const f32x4 c0 = *(const f32x4*)(rp + pos * 16), c1 = *(const f32x4*)(rp + pos * 16 + 4);
;                             const f32x4 s0 = *(const f32x4*)(rp + 2048 + pos * 16), s1 = *(const f32x4*)(rp + 2048 + pos * 16 + 4);
;                             f32x4 o0, o1;
; #pragma unroll
;                             for (int i = 0; i < 4; ++i) { const float p0 = __uint_as_float((unsigned)__builtin_amdgcn_ds_bpermute(paddr, (int)__float_as_uint(v0[i]))) * s0[i], p1 = __uint_as_float((unsigned)__builtin_amdgcn_ds_bpermute(paddr, (int)__float_as_uint(v1[i]))) * s1[i];
;                                 o0[i] = v0[i] * c0[i] + (fq >= 2 ? p0 : -p0); o1[i] = v1[i] * c1[i] + (fq >= 2 ? p1 : -p1); }
;                             v0 = o0; v1 = o1;
;                         }
;                     }
;                     u32x4 w; w.x = pkbf(v0[0], v0[1]); w.y = pkbf(v0[2], v0[3]); w.z = pkbf(v1[0], v1[1]); w.w = pkbf(v1[2], v1[3]);
;                     *(u32x4*)(dst + (size_t)row * pitch + 32 * bj) = w;
.Lqkv_rope:
	v_lshl_add_u64 v[214:215], v[136:137], 0, s[82:83]
	global_load_dwordx4 v[162:165], v[214:215], off
	global_load_dwordx4 v[166:169], v[214:215], off offset:16
	global_load_dwordx4 v[170:173], v[214:215], off offset:128
	global_load_dwordx4 v[174:177], v[214:215], off offset:144
	v_lshl_add_u32 v221, s12, 8, v158
	v_and_b32_e32 v218, 0x1fc0, v221
	v_mov_b32_e32 v219, 0
	v_lshl_add_u64 v[214:215], v[138:139], 0, v[218:219]
	v_lshl_add_u64 v[216:217], v[140:141], 0, v[218:219]
	global_load_dwordx4 v[178:181], v[214:215], off
	global_load_dwordx4 v[182:185], v[214:215], off offset:16
	global_load_dwordx4 v[186:189], v[216:217], off
	global_load_dwordx4 v[190:193], v[216:217], off offset:16
	v_and_b32_e32 v218, 63, v221
	v_lshlrev_b32_e32 v218, 6, v218
	v_mov_b32_e32 v219, 0
	v_lshl_add_u64 v[214:215], v[138:139], 0, v[218:219]
	v_lshl_add_u64 v[216:217], v[140:141], 0, v[218:219]
	global_load_dwordx4 v[198:201], v[214:215], off
	global_load_dwordx4 v[202:205], v[214:215], off offset:16
	global_load_dwordx4 v[206:209], v[216:217], off
	global_load_dwordx4 v[210:213], v[216:217], off offset:16
	v_mul_f32_e32 v143, v125, v125
	v_mul_f32_e32 v144, v127, v127
	v_fmac_f32_e32 v143, v124, v124
	v_fmac_f32_e32 v144, v126, v126
	v_add_f32_e32 v142, v143, v144
	v_mul_f32_e32 v143, v121, v121
	v_mul_f32_e32 v144, v123, v123
	v_fmac_f32_e32 v143, v120, v120
	v_fmac_f32_e32 v144, v122, v122
	v_add_f32_e32 v143, v143, v144
	v_add_f32_e32 v142, v142, v143
	v_mul_f32_e32 v143, v117, v117
	v_mul_f32_e32 v144, v119, v119
	v_fmac_f32_e32 v143, v116, v116
	v_fmac_f32_e32 v144, v118, v118
	v_add_f32_e32 v143, v143, v144
	v_add_f32_e32 v142, v142, v143
	v_mul_f32_e32 v143, v113, v113
	v_mul_f32_e32 v144, v115, v115
	v_fmac_f32_e32 v143, v112, v112
	v_fmac_f32_e32 v144, v114, v114
	v_add_f32_e32 v143, v143, v144
	v_add_f32_e32 v142, v142, v143
	v_mov_b32_e32 v143, v142
	s_nop 1
	v_permlane16_swap_b32_e32 v142, v143
	v_add_f32_e32 v142, v142, v143
	v_mov_b32_e32 v143, v142
	s_nop 1
	v_permlane32_swap_b32_e32 v142, v143
	v_add_f32_e32 v142, v142, v143
	v_fmamk_f32 v144, v142, 0x3c800000, v153
	v_rsq_f32_e32 v144, v144
	s_nop 0
	s_waitcnt vmcnt(8)
	v_pk_mul_f32 v[124:125], v[124:125], v[144:145] op_sel_hi:[1,0]
	v_pk_mul_f32 v[126:127], v[126:127], v[144:145] op_sel_hi:[1,0]
	v_pk_mul_f32 v[124:125], v[124:125], v[162:163]
	v_pk_mul_f32 v[126:127], v[126:127], v[164:165]
	v_pk_mul_f32 v[120:121], v[120:121], v[144:145] op_sel_hi:[1,0]
	v_pk_mul_f32 v[122:123], v[122:123], v[144:145] op_sel_hi:[1,0]
	v_pk_mul_f32 v[120:121], v[120:121], v[166:167]
	v_pk_mul_f32 v[122:123], v[122:123], v[168:169]
	v_pk_mul_f32 v[116:117], v[116:117], v[144:145] op_sel_hi:[1,0]
	v_pk_mul_f32 v[118:119], v[118:119], v[144:145] op_sel_hi:[1,0]
	v_pk_mul_f32 v[116:117], v[116:117], v[170:171]
	v_pk_mul_f32 v[118:119], v[118:119], v[172:173]
	v_pk_mul_f32 v[112:113], v[112:113], v[144:145] op_sel_hi:[1,0]
	v_pk_mul_f32 v[114:115], v[114:115], v[144:145] op_sel_hi:[1,0]
	v_pk_mul_f32 v[112:113], v[112:113], v[174:175]
	v_pk_mul_f32 v[114:115], v[114:115], v[176:177]
	ds_bpermute_b32 v214, v160, v124
	ds_bpermute_b32 v215, v160, v125
	ds_bpermute_b32 v216, v160, v126
	ds_bpermute_b32 v217, v160, v127
	ds_bpermute_b32 v218, v160, v120
	ds_bpermute_b32 v219, v160, v121
	ds_bpermute_b32 v220, v160, v122
	ds_bpermute_b32 v221, v160, v123
	s_waitcnt vmcnt(4)
	s_waitcnt lgkmcnt(0)
	v_pk_mul_f32 v[214:215], v[186:187], v[214:215]
	v_pk_mul_f32 v[216:217], v[188:189], v[216:217]
	v_cndmask_b32_e64 v214, -v214, v214, s[6:7]
	v_cndmask_b32_e64 v215, -v215, v215, s[6:7]
	v_cndmask_b32_e64 v216, -v216, v216, s[6:7]
	v_cndmask_b32_e64 v217, -v217, v217, s[6:7]
	v_pk_fma_f32 v[124:125], v[124:125], v[178:179], v[214:215]
	v_pk_fma_f32 v[126:127], v[126:127], v[180:181], v[216:217]
	v_pk_mul_f32 v[218:219], v[190:191], v[218:219]
	v_pk_mul_f32 v[220:221], v[192:193], v[220:221]
	v_cndmask_b32_e64 v218, -v218, v218, s[6:7]
	v_cndmask_b32_e64 v219, -v219, v219, s[6:7]
	v_cndmask_b32_e64 v220, -v220, v220, s[6:7]
	v_cndmask_b32_e64 v221, -v221, v221, s[6:7]
	v_pk_fma_f32 v[120:121], v[120:121], v[182:183], v[218:219]
	v_pk_fma_f32 v[122:123], v[122:123], v[184:185], v[220:221]
	v_lshl_add_u32 v142, s12, 8, v158
	v_lshl_add_u32 v142, v142, s13, v154
	v_cvt_pk_bf16_f32 v124, v124, v125
	v_cvt_pk_bf16_f32 v125, v126, v127
	v_cvt_pk_bf16_f32 v126, v120, v121
	v_cvt_pk_bf16_f32 v127, v122, v123
	global_store_dwordx4 v142, v[124:127], s[36:37]
	ds_bpermute_b32 v214, v160, v116
	ds_bpermute_b32 v215, v160, v117
	ds_bpermute_b32 v216, v160, v118
	ds_bpermute_b32 v217, v160, v119
	ds_bpermute_b32 v218, v160, v112
	ds_bpermute_b32 v219, v160, v113
	ds_bpermute_b32 v220, v160, v114
	ds_bpermute_b32 v221, v160, v115
	s_waitcnt vmcnt(1)
	s_waitcnt lgkmcnt(0)
; __device__ __forceinline__ unsigned pkbf(float lo, float hi) { f32x2_t v = {lo, hi}; bf16x2_t b = __builtin_convertvector(v, bf16x2_t); return __builtin_bit_cast(unsigned, b); }
;     __device__ __forceinline__ void operator()(const f32x4 (&acc)[2][2][4][2], const pg8::Unit& u, int wr, int wc, int fr, int fq) const {
;     ...
;                 const int t = row & (SEQ - 1);
; #pragma unroll
;                 for (int bj = 0; bj < 2; ++bj) {
;                     f32x4 v0 = acc[ai][bj][m][0], v1 = acc[ai][bj][m][1];
;                     if (kind < 2) {
;                         v0 = v0 * rs * *(const f32x4*)(gp + 32 * bj); v1 = v1 * rs * *(const f32x4*)(gp + 32 * bj + 4);
;                         if (dorope) {
;                             const int pos = bj ? (t & 63) : (t >> 6);
;                             const f32x4 c0 = *(const f32x4*)(rp + pos * 16), c1 = *(const f32x4*)(rp + pos * 16 + 4);
;                             const f32x4 s0 = *(const f32x4*)(rp + 2048 + pos * 16), s1 = *(const f32x4*)(rp + 2048 + pos * 16 + 4);
;                             f32x4 o0, o1;
; #pragma unroll
;                             for (int i = 0; i < 4; ++i) { const float p0 = __uint_as_float((unsigned)__builtin_amdgcn_ds_bpermute(paddr, (int)__float_as_uint(v0[i]))) * s0[i], p1 = __uint_as_float((unsigned)__builtin_amdgcn_ds_bpermute(paddr, (int)__float_as_uint(v1[i]))) * s1[i];
;                                 o0[i] = v0[i] * c0[i] + (fq >= 2 ? p0 : -p0); o1[i] = v1[i] * c1[i] + (fq >= 2 ? p1 : -p1); }
;                             v0 = o0; v1 = o1;
;                         }
;                     }
;                     u32x4 w; w.x = pkbf(v0[0], v0[1]); w.y = pkbf(v0[2], v0[3]); w.z = pkbf(v1[0], v1[1]); w.w = pkbf(v1[2], v1[3]);
;                     *(u32x4*)(dst + (size_t)row * pitch + 32 * bj) = w;
	v_pk_mul_f32 v[214:215], v[206:207], v[214:215]
	v_pk_mul_f32 v[216:217], v[208:209], v[216:217]
	v_cndmask_b32_e64 v214, -v214, v214, s[6:7]
	v_cndmask_b32_e64 v215, -v215, v215, s[6:7]
	v_cndmask_b32_e64 v216, -v216, v216, s[6:7]
	v_cndmask_b32_e64 v217, -v217, v217, s[6:7]
	v_pk_fma_f32 v[116:117], v[116:117], v[198:199], v[214:215]
	v_pk_fma_f32 v[118:119], v[118:119], v[200:201], v[216:217]
	v_pk_mul_f32 v[218:219], v[210:211], v[218:219]
	v_pk_mul_f32 v[220:221], v[212:213], v[220:221]
	v_cndmask_b32_e64 v218, -v218, v218, s[6:7]
	v_cndmask_b32_e64 v219, -v219, v219, s[6:7]
	v_cndmask_b32_e64 v220, -v220, v220, s[6:7]
	v_cndmask_b32_e64 v221, -v221, v221, s[6:7]
	v_pk_fma_f32 v[112:113], v[112:113], v[202:203], v[218:219]
	v_pk_fma_f32 v[114:115], v[114:115], v[204:205], v[220:221]
	v_cvt_pk_bf16_f32 v116, v116, v117
	v_cvt_pk_bf16_f32 v117, v118, v119
	v_cvt_pk_bf16_f32 v118, v112, v113
	v_cvt_pk_bf16_f32 v119, v114, v115
	global_store_dwordx4 v142, v[116:119], s[36:37] offset:64
	v_lshl_add_u32 v221, s12, 8, v158
	v_add_u32_e32 v221, 16, v221
	v_and_b32_e32 v218, 63, v221
	v_lshlrev_b32_e32 v218, 6, v218
	v_mov_b32_e32 v219, 0
	v_lshl_add_u64 v[214:215], v[138:139], 0, v[218:219]
	v_lshl_add_u64 v[216:217], v[140:141], 0, v[218:219]
	global_load_dwordx4 v[198:201], v[214:215], off
	global_load_dwordx4 v[202:205], v[214:215], off offset:16
	global_load_dwordx4 v[206:209], v[216:217], off
	global_load_dwordx4 v[210:213], v[216:217], off offset:16
	v_mul_f32_e32 v143, v109, v109
	v_mul_f32_e32 v144, v111, v111
	v_fmac_f32_e32 v143, v108, v108
	v_fmac_f32_e32 v144, v110, v110
	v_add_f32_e32 v142, v143, v144
	v_mul_f32_e32 v143, v105, v105
	v_mul_f32_e32 v144, v107, v107
	v_fmac_f32_e32 v143, v104, v104
	v_fmac_f32_e32 v144, v106, v106
	v_add_f32_e32 v143, v143, v144
	v_add_f32_e32 v142, v142, v143
	v_mul_f32_e32 v143, v101, v101
	v_mul_f32_e32 v144, v103, v103
	v_fmac_f32_e32 v143, v100, v100
	v_fmac_f32_e32 v144, v102, v102
	v_add_f32_e32 v143, v143, v144
	v_add_f32_e32 v142, v142, v143
	v_mul_f32_e32 v143, v97, v97
	v_mul_f32_e32 v144, v99, v99
	v_fmac_f32_e32 v143, v96, v96
	v_fmac_f32_e32 v144, v98, v98
	v_add_f32_e32 v143, v143, v144
	v_add_f32_e32 v142, v142, v143
	v_mov_b32_e32 v143, v142
	s_nop 1
	v_permlane16_swap_b32_e32 v142, v143
	v_add_f32_e32 v142, v142, v143
	v_mov_b32_e32 v143, v142
	s_nop 1
	v_permlane32_swap_b32_e32 v142, v143
	v_add_f32_e32 v142, v142, v143
	v_fmamk_f32 v144, v142, 0x3c800000, v153
	v_rsq_f32_e32 v144, v144
	s_nop 0
	v_pk_mul_f32 v[108:109], v[108:109], v[144:145] op_sel_hi:[1,0]
	v_pk_mul_f32 v[110:111], v[110:111], v[144:145] op_sel_hi:[1,0]
	v_pk_mul_f32 v[108:109], v[108:109], v[162:163]
	v_pk_mul_f32 v[110:111], v[110:111], v[164:165]
	v_pk_mul_f32 v[104:105], v[104:105], v[144:145] op_sel_hi:[1,0]
	v_pk_mul_f32 v[106:107], v[106:107], v[144:145] op_sel_hi:[1,0]
	v_pk_mul_f32 v[104:105], v[104:105], v[166:167]
	v_pk_mul_f32 v[106:107], v[106:107], v[168:169]
	v_pk_mul_f32 v[100:101], v[100:101], v[144:145] op_sel_hi:[1,0]
	v_pk_mul_f32 v[102:103], v[102:103], v[144:145] op_sel_hi:[1,0]
	v_pk_mul_f32 v[100:101], v[100:101], v[170:171]
	v_pk_mul_f32 v[102:103], v[102:103], v[172:173]
	v_pk_mul_f32 v[96:97], v[96:97], v[144:145] op_sel_hi:[1,0]
	v_pk_mul_f32 v[98:99], v[98:99], v[144:145] op_sel_hi:[1,0]
	v_pk_mul_f32 v[96:97], v[96:97], v[174:175]
	v_pk_mul_f32 v[98:99], v[98:99], v[176:177]
	ds_bpermute_b32 v214, v160, v108
	ds_bpermute_b32 v215, v160, v109
	ds_bpermute_b32 v216, v160, v110
	ds_bpermute_b32 v217, v160, v111
	ds_bpermute_b32 v218, v160, v104
	ds_bpermute_b32 v219, v160, v105
	ds_bpermute_b32 v220, v160, v106
	ds_bpermute_b32 v221, v160, v107
	s_waitcnt lgkmcnt(0)
	v_pk_mul_f32 v[214:215], v[186:187], v[214:215]
	v_pk_mul_f32 v[216:217], v[188:189], v[216:217]
	v_cndmask_b32_e64 v214, -v214, v214, s[6:7]
	v_cndmask_b32_e64 v215, -v215, v215, s[6:7]
	v_cndmask_b32_e64 v216, -v216, v216, s[6:7]
	v_cndmask_b32_e64 v217, -v217, v217, s[6:7]
	v_pk_fma_f32 v[108:109], v[108:109], v[178:179], v[214:215]
	v_pk_fma_f32 v[110:111], v[110:111], v[180:181], v[216:217]
	v_pk_mul_f32 v[218:219], v[190:191], v[218:219]
	v_pk_mul_f32 v[220:221], v[192:193], v[220:221]
	v_cndmask_b32_e64 v218, -v218, v218, s[6:7]
	v_cndmask_b32_e64 v219, -v219, v219, s[6:7]
	v_cndmask_b32_e64 v220, -v220, v220, s[6:7]
	v_cndmask_b32_e64 v221, -v221, v221, s[6:7]
	v_pk_fma_f32 v[104:105], v[104:105], v[182:183], v[218:219]
	v_pk_fma_f32 v[106:107], v[106:107], v[184:185], v[220:221]
	v_lshl_add_u32 v142, s12, 8, v158
	v_add_u32_e32 v142, 16, v142
	v_lshl_add_u32 v142, v142, s13, v154
	v_cvt_pk_bf16_f32 v108, v108, v109
	v_cvt_pk_bf16_f32 v109, v110, v111
	v_cvt_pk_bf16_f32 v110, v104, v105
	v_cvt_pk_bf16_f32 v111, v106, v107
	global_store_dwordx4 v142, v[108:111], s[36:37]
	ds_bpermute_b32 v214, v160, v100
	ds_bpermute_b32 v215, v160, v101
	ds_bpermute_b32 v216, v160, v102
	ds_bpermute_b32 v217, v160, v103
	ds_bpermute_b32 v218, v160, v96
	ds_bpermute_b32 v219, v160, v97
	ds_bpermute_b32 v220, v160, v98
	ds_bpermute_b32 v221, v160, v99
	s_waitcnt vmcnt(1)
	s_waitcnt lgkmcnt(0)
; __device__ __forceinline__ unsigned pkbf(float lo, float hi) { f32x2_t v = {lo, hi}; bf16x2_t b = __builtin_convertvector(v, bf16x2_t); return __builtin_bit_cast(unsigned, b); }
;     __device__ __forceinline__ void operator()(const f32x4 (&acc)[2][2][4][2], const pg8::Unit& u, int wr, int wc, int fr, int fq) const {
;     ...
;                 const int t = row & (SEQ - 1);
; #pragma unroll
;                 for (int bj = 0; bj < 2; ++bj) {
;                     f32x4 v0 = acc[ai][bj][m][0], v1 = acc[ai][bj][m][1];
;                     if (kind < 2) {
;                         v0 = v0 * rs * *(const f32x4*)(gp + 32 * bj); v1 = v1 * rs * *(const f32x4*)(gp + 32 * bj + 4);
;                         if (dorope) {
;                             const int pos = bj ? (t & 63) : (t >> 6);
;                             const f32x4 c0 = *(const f32x4*)(rp + pos * 16), c1 = *(const f32x4*)(rp + pos * 16 + 4);
;                             const f32x4 s0 = *(const f32x4*)(rp + 2048 + pos * 16), s1 = *(const f32x4*)(rp + 2048 + pos * 16 + 4);
;                             f32x4 o0, o1;
; #pragma unroll
;                             for (int i = 0; i < 4; ++i) { const float p0 = __uint_as_float((unsigned)__builtin_amdgcn_ds_bpermute(paddr, (int)__float_as_uint(v0[i]))) * s0[i], p1 = __uint_as_float((unsigned)__builtin_amdgcn_ds_bpermute(paddr, (int)__float_as_uint(v1[i]))) * s1[i];
;                                 o0[i] = v0[i] * c0[i] + (fq >= 2 ? p0 : -p0); o1[i] = v1[i] * c1[i] + (fq >= 2 ? p1 : -p1); }
;                             v0 = o0; v1 = o1;
;                         }
;                     }
;                     u32x4 w; w.x = pkbf(v0[0], v0[1]); w.y = pkbf(v0[2], v0[3]); w.z = pkbf(v1[0], v1[1]); w.w = pkbf(v1[2], v1[3]);
;                     *(u32x4*)(dst + (size_t)row * pitch + 32 * bj) = w;
	v_pk_mul_f32 v[214:215], v[206:207], v[214:215]
	v_pk_mul_f32 v[216:217], v[208:209], v[216:217]
	v_cndmask_b32_e64 v214, -v214, v214, s[6:7]
	v_cndmask_b32_e64 v215, -v215, v215, s[6:7]
	v_cndmask_b32_e64 v216, -v216, v216, s[6:7]
	v_cndmask_b32_e64 v217, -v217, v217, s[6:7]
	v_pk_fma_f32 v[100:101], v[100:101], v[198:199], v[214:215]
	v_pk_fma_f32 v[102:103], v[102:103], v[200:201], v[216:217]
	v_pk_mul_f32 v[218:219], v[210:211], v[218:219]
	v_pk_mul_f32 v[220:221], v[212:213], v[220:221]
	v_cndmask_b32_e64 v218, -v218, v218, s[6:7]
	v_cndmask_b32_e64 v219, -v219, v219, s[6:7]
	v_cndmask_b32_e64 v220, -v220, v220, s[6:7]
	v_cndmask_b32_e64 v221, -v221, v221, s[6:7]
	v_pk_fma_f32 v[96:97], v[96:97], v[202:203], v[218:219]
	v_pk_fma_f32 v[98:99], v[98:99], v[204:205], v[220:221]
	v_cvt_pk_bf16_f32 v100, v100, v101
	v_cvt_pk_bf16_f32 v101, v102, v103
	v_cvt_pk_bf16_f32 v102, v96, v97
	v_cvt_pk_bf16_f32 v103, v98, v99
	global_store_dwordx4 v142, v[100:103], s[36:37] offset:64
	v_lshl_add_u32 v221, s12, 8, v158
	v_add_u32_e32 v221, 32, v221
	v_and_b32_e32 v218, 63, v221
	v_lshlrev_b32_e32 v218, 6, v218
	v_mov_b32_e32 v219, 0
	v_lshl_add_u64 v[214:215], v[138:139], 0, v[218:219]
	v_lshl_add_u64 v[216:217], v[140:141], 0, v[218:219]
	global_load_dwordx4 v[198:201], v[214:215], off
	global_load_dwordx4 v[202:205], v[214:215], off offset:16
	global_load_dwordx4 v[206:209], v[216:217], off
	global_load_dwordx4 v[210:213], v[216:217], off offset:16
	v_mul_f32_e32 v143, v93, v93
	v_mul_f32_e32 v144, v95, v95
	v_fmac_f32_e32 v143, v92, v92
	v_fmac_f32_e32 v144, v94, v94
	v_add_f32_e32 v142, v143, v144
	v_mul_f32_e32 v143, v89, v89
	v_mul_f32_e32 v144, v91, v91
	v_fmac_f32_e32 v143, v88, v88
	v_fmac_f32_e32 v144, v90, v90
	v_add_f32_e32 v143, v143, v144
	v_add_f32_e32 v142, v142, v143
	v_mul_f32_e32 v143, v85, v85
	v_mul_f32_e32 v144, v87, v87
	v_fmac_f32_e32 v143, v84, v84
	v_fmac_f32_e32 v144, v86, v86
	v_add_f32_e32 v143, v143, v144
	v_add_f32_e32 v142, v142, v143
	v_mul_f32_e32 v143, v81, v81
	v_mul_f32_e32 v144, v83, v83
	v_fmac_f32_e32 v143, v80, v80
	v_fmac_f32_e32 v144, v82, v82
	v_add_f32_e32 v143, v143, v144
	v_add_f32_e32 v142, v142, v143
	v_mov_b32_e32 v143, v142
	s_nop 1
	v_permlane16_swap_b32_e32 v142, v143
	v_add_f32_e32 v142, v142, v143
	v_mov_b32_e32 v143, v142
	s_nop 1
	v_permlane32_swap_b32_e32 v142, v143
	v_add_f32_e32 v142, v142, v143
	v_fmamk_f32 v144, v142, 0x3c800000, v153
	v_rsq_f32_e32 v144, v144
	s_nop 0
	v_pk_mul_f32 v[92:93], v[92:93], v[144:145] op_sel_hi:[1,0]
	v_pk_mul_f32 v[94:95], v[94:95], v[144:145] op_sel_hi:[1,0]
	v_pk_mul_f32 v[92:93], v[92:93], v[162:163]
	v_pk_mul_f32 v[94:95], v[94:95], v[164:165]
	v_pk_mul_f32 v[88:89], v[88:89], v[144:145] op_sel_hi:[1,0]
	v_pk_mul_f32 v[90:91], v[90:91], v[144:145] op_sel_hi:[1,0]
	v_pk_mul_f32 v[88:89], v[88:89], v[166:167]
	v_pk_mul_f32 v[90:91], v[90:91], v[168:169]
	v_pk_mul_f32 v[84:85], v[84:85], v[144:145] op_sel_hi:[1,0]
	v_pk_mul_f32 v[86:87], v[86:87], v[144:145] op_sel_hi:[1,0]
	v_pk_mul_f32 v[84:85], v[84:85], v[170:171]
	v_pk_mul_f32 v[86:87], v[86:87], v[172:173]
	v_pk_mul_f32 v[80:81], v[80:81], v[144:145] op_sel_hi:[1,0]
	v_pk_mul_f32 v[82:83], v[82:83], v[144:145] op_sel_hi:[1,0]
	v_pk_mul_f32 v[80:81], v[80:81], v[174:175]
	v_pk_mul_f32 v[82:83], v[82:83], v[176:177]
	ds_bpermute_b32 v214, v160, v92
	ds_bpermute_b32 v215, v160, v93
	ds_bpermute_b32 v216, v160, v94
	ds_bpermute_b32 v217, v160, v95
	ds_bpermute_b32 v218, v160, v88
	ds_bpermute_b32 v219, v160, v89
	ds_bpermute_b32 v220, v160, v90
	ds_bpermute_b32 v221, v160, v91
	s_waitcnt lgkmcnt(0)
	v_pk_mul_f32 v[214:215], v[186:187], v[214:215]
	v_pk_mul_f32 v[216:217], v[188:189], v[216:217]
	v_cndmask_b32_e64 v214, -v214, v214, s[6:7]
	v_cndmask_b32_e64 v215, -v215, v215, s[6:7]
	v_cndmask_b32_e64 v216, -v216, v216, s[6:7]
	v_cndmask_b32_e64 v217, -v217, v217, s[6:7]
	v_pk_fma_f32 v[92:93], v[92:93], v[178:179], v[214:215]
	v_pk_fma_f32 v[94:95], v[94:95], v[180:181], v[216:217]
	v_pk_mul_f32 v[218:219], v[190:191], v[218:219]
	v_pk_mul_f32 v[220:221], v[192:193], v[220:221]
	v_cndmask_b32_e64 v218, -v218, v218, s[6:7]
	v_cndmask_b32_e64 v219, -v219, v219, s[6:7]
	v_cndmask_b32_e64 v220, -v220, v220, s[6:7]
	v_cndmask_b32_e64 v221, -v221, v221, s[6:7]
	v_pk_fma_f32 v[88:89], v[88:89], v[182:183], v[218:219]
	v_pk_fma_f32 v[90:91], v[90:91], v[184:185], v[220:221]
	v_lshl_add_u32 v142, s12, 8, v158
	v_add_u32_e32 v142, 32, v142
	v_lshl_add_u32 v142, v142, s13, v154
	v_cvt_pk_bf16_f32 v92, v92, v93
	v_cvt_pk_bf16_f32 v93, v94, v95
	v_cvt_pk_bf16_f32 v94, v88, v89
	v_cvt_pk_bf16_f32 v95, v90, v91
	global_store_dwordx4 v142, v[92:95], s[36:37]
	ds_bpermute_b32 v214, v160, v84
	ds_bpermute_b32 v215, v160, v85
	ds_bpermute_b32 v216, v160, v86
	ds_bpermute_b32 v217, v160, v87
	ds_bpermute_b32 v218, v160, v80
	ds_bpermute_b32 v219, v160, v81
	ds_bpermute_b32 v220, v160, v82
	ds_bpermute_b32 v221, v160, v83
	s_waitcnt vmcnt(1)
	s_waitcnt lgkmcnt(0)
; __device__ __forceinline__ unsigned pkbf(float lo, float hi) { f32x2_t v = {lo, hi}; bf16x2_t b = __builtin_convertvector(v, bf16x2_t); return __builtin_bit_cast(unsigned, b); }
;     __device__ __forceinline__ void operator()(const f32x4 (&acc)[2][2][4][2], const pg8::Unit& u, int wr, int wc, int fr, int fq) const {
;     ...
;                 const int t = row & (SEQ - 1);
; #pragma unroll
;                 for (int bj = 0; bj < 2; ++bj) {
;                     f32x4 v0 = acc[ai][bj][m][0], v1 = acc[ai][bj][m][1];
;                     if (kind < 2) {
;                         v0 = v0 * rs * *(const f32x4*)(gp + 32 * bj); v1 = v1 * rs * *(const f32x4*)(gp + 32 * bj + 4);
;                         if (dorope) {
;                             const int pos = bj ? (t & 63) : (t >> 6);
;                             const f32x4 c0 = *(const f32x4*)(rp + pos * 16), c1 = *(const f32x4*)(rp + pos * 16 + 4);
;                             const f32x4 s0 = *(const f32x4*)(rp + 2048 + pos * 16), s1 = *(const f32x4*)(rp + 2048 + pos * 16 + 4);
;                             f32x4 o0, o1;
; #pragma unroll
;                             for (int i = 0; i < 4; ++i) { const float p0 = __uint_as_float((unsigned)__builtin_amdgcn_ds_bpermute(paddr, (int)__float_as_uint(v0[i]))) * s0[i], p1 = __uint_as_float((unsigned)__builtin_amdgcn_ds_bpermute(paddr, (int)__float_as_uint(v1[i]))) * s1[i];
;                                 o0[i] = v0[i] * c0[i] + (fq >= 2 ? p0 : -p0); o1[i] = v1[i] * c1[i] + (fq >= 2 ? p1 : -p1); }
;                             v0 = o0; v1 = o1;
;                         }
;                     }
;                     u32x4 w; w.x = pkbf(v0[0], v0[1]); w.y = pkbf(v0[2], v0[3]); w.z = pkbf(v1[0], v1[1]); w.w = pkbf(v1[2], v1[3]);
;                     *(u32x4*)(dst + (size_t)row * pitch + 32 * bj) = w;
	v_pk_mul_f32 v[214:215], v[206:207], v[214:215]
	v_pk_mul_f32 v[216:217], v[208:209], v[216:217]
	v_cndmask_b32_e64 v214, -v214, v214, s[6:7]
	v_cndmask_b32_e64 v215, -v215, v215, s[6:7]
	v_cndmask_b32_e64 v216, -v216, v216, s[6:7]
	v_cndmask_b32_e64 v217, -v217, v217, s[6:7]
	v_pk_fma_f32 v[84:85], v[84:85], v[198:199], v[214:215]
	v_pk_fma_f32 v[86:87], v[86:87], v[200:201], v[216:217]
	v_pk_mul_f32 v[218:219], v[210:211], v[218:219]
	v_pk_mul_f32 v[220:221], v[212:213], v[220:221]
	v_cndmask_b32_e64 v218, -v218, v218, s[6:7]
	v_cndmask_b32_e64 v219, -v219, v219, s[6:7]
	v_cndmask_b32_e64 v220, -v220, v220, s[6:7]
	v_cndmask_b32_e64 v221, -v221, v221, s[6:7]
	v_pk_fma_f32 v[80:81], v[80:81], v[202:203], v[218:219]
	v_pk_fma_f32 v[82:83], v[82:83], v[204:205], v[220:221]
	v_cvt_pk_bf16_f32 v84, v84, v85
	v_cvt_pk_bf16_f32 v85, v86, v87
	v_cvt_pk_bf16_f32 v86, v80, v81
	v_cvt_pk_bf16_f32 v87, v82, v83
	global_store_dwordx4 v142, v[84:87], s[36:37] offset:64
	v_lshl_add_u32 v221, s12, 8, v158
	v_add_u32_e32 v221, 48, v221
	v_and_b32_e32 v218, 63, v221
	v_lshlrev_b32_e32 v218, 6, v218
	v_mov_b32_e32 v219, 0
	v_lshl_add_u64 v[214:215], v[138:139], 0, v[218:219]
	v_lshl_add_u64 v[216:217], v[140:141], 0, v[218:219]
	global_load_dwordx4 v[198:201], v[214:215], off
	global_load_dwordx4 v[202:205], v[214:215], off offset:16
	global_load_dwordx4 v[206:209], v[216:217], off
	global_load_dwordx4 v[210:213], v[216:217], off offset:16
	v_mul_f32_e32 v143, v77, v77
	v_mul_f32_e32 v144, v79, v79
	v_fmac_f32_e32 v143, v76, v76
	v_fmac_f32_e32 v144, v78, v78
	v_add_f32_e32 v142, v143, v144
	v_mul_f32_e32 v143, v73, v73
	v_mul_f32_e32 v144, v75, v75
	v_fmac_f32_e32 v143, v72, v72
	v_fmac_f32_e32 v144, v74, v74
	v_add_f32_e32 v143, v143, v144
	v_add_f32_e32 v142, v142, v143
	v_mul_f32_e32 v143, v69, v69
	v_mul_f32_e32 v144, v71, v71
	v_fmac_f32_e32 v143, v68, v68
	v_fmac_f32_e32 v144, v70, v70
	v_add_f32_e32 v143, v143, v144
	v_add_f32_e32 v142, v142, v143
	v_mul_f32_e32 v143, v65, v65
	v_mul_f32_e32 v144, v67, v67
	v_fmac_f32_e32 v143, v64, v64
	v_fmac_f32_e32 v144, v66, v66
	v_add_f32_e32 v143, v143, v144
	v_add_f32_e32 v142, v142, v143
	v_mov_b32_e32 v143, v142
	s_nop 1
	v_permlane16_swap_b32_e32 v142, v143
	v_add_f32_e32 v142, v142, v143
	v_mov_b32_e32 v143, v142
	s_nop 1
	v_permlane32_swap_b32_e32 v142, v143
	v_add_f32_e32 v142, v142, v143
	v_fmamk_f32 v144, v142, 0x3c800000, v153
	v_rsq_f32_e32 v144, v144
	s_nop 0
	v_pk_mul_f32 v[76:77], v[76:77], v[144:145] op_sel_hi:[1,0]
	v_pk_mul_f32 v[78:79], v[78:79], v[144:145] op_sel_hi:[1,0]
	v_pk_mul_f32 v[76:77], v[76:77], v[162:163]
	v_pk_mul_f32 v[78:79], v[78:79], v[164:165]
	v_pk_mul_f32 v[72:73], v[72:73], v[144:145] op_sel_hi:[1,0]
	v_pk_mul_f32 v[74:75], v[74:75], v[144:145] op_sel_hi:[1,0]
	v_pk_mul_f32 v[72:73], v[72:73], v[166:167]
	v_pk_mul_f32 v[74:75], v[74:75], v[168:169]
	v_pk_mul_f32 v[68:69], v[68:69], v[144:145] op_sel_hi:[1,0]
	v_pk_mul_f32 v[70:71], v[70:71], v[144:145] op_sel_hi:[1,0]
	v_pk_mul_f32 v[68:69], v[68:69], v[170:171]
	v_pk_mul_f32 v[70:71], v[70:71], v[172:173]
	v_pk_mul_f32 v[64:65], v[64:65], v[144:145] op_sel_hi:[1,0]
	v_pk_mul_f32 v[66:67], v[66:67], v[144:145] op_sel_hi:[1,0]
	v_pk_mul_f32 v[64:65], v[64:65], v[174:175]
	v_pk_mul_f32 v[66:67], v[66:67], v[176:177]
	ds_bpermute_b32 v214, v160, v76
	ds_bpermute_b32 v215, v160, v77
	ds_bpermute_b32 v216, v160, v78
	ds_bpermute_b32 v217, v160, v79
	ds_bpermute_b32 v218, v160, v72
	ds_bpermute_b32 v219, v160, v73
	ds_bpermute_b32 v220, v160, v74
	ds_bpermute_b32 v221, v160, v75
	s_waitcnt lgkmcnt(0)
	v_pk_mul_f32 v[214:215], v[186:187], v[214:215]
	v_pk_mul_f32 v[216:217], v[188:189], v[216:217]
	v_cndmask_b32_e64 v214, -v214, v214, s[6:7]
	v_cndmask_b32_e64 v215, -v215, v215, s[6:7]
	v_cndmask_b32_e64 v216, -v216, v216, s[6:7]
	v_cndmask_b32_e64 v217, -v217, v217, s[6:7]
	v_pk_fma_f32 v[76:77], v[76:77], v[178:179], v[214:215]
	v_pk_fma_f32 v[78:79], v[78:79], v[180:181], v[216:217]
	v_pk_mul_f32 v[218:219], v[190:191], v[218:219]
	v_pk_mul_f32 v[220:221], v[192:193], v[220:221]
	v_cndmask_b32_e64 v218, -v218, v218, s[6:7]
	v_cndmask_b32_e64 v219, -v219, v219, s[6:7]
	v_cndmask_b32_e64 v220, -v220, v220, s[6:7]
	v_cndmask_b32_e64 v221, -v221, v221, s[6:7]
	v_pk_fma_f32 v[72:73], v[72:73], v[182:183], v[218:219]
	v_pk_fma_f32 v[74:75], v[74:75], v[184:185], v[220:221]
	v_lshl_add_u32 v142, s12, 8, v158
	v_add_u32_e32 v142, 48, v142
	v_lshl_add_u32 v142, v142, s13, v154
	v_cvt_pk_bf16_f32 v76, v76, v77
	v_cvt_pk_bf16_f32 v77, v78, v79
	v_cvt_pk_bf16_f32 v78, v72, v73
	v_cvt_pk_bf16_f32 v79, v74, v75
	global_store_dwordx4 v142, v[76:79], s[36:37]
	ds_bpermute_b32 v214, v160, v68
	ds_bpermute_b32 v215, v160, v69
	ds_bpermute_b32 v216, v160, v70
	ds_bpermute_b32 v217, v160, v71
	ds_bpermute_b32 v218, v160, v64
	ds_bpermute_b32 v219, v160, v65
	ds_bpermute_b32 v220, v160, v66
	ds_bpermute_b32 v221, v160, v67
	s_waitcnt vmcnt(1)
	s_waitcnt lgkmcnt(0)
; __device__ __forceinline__ unsigned pkbf(float lo, float hi) { f32x2_t v = {lo, hi}; bf16x2_t b = __builtin_convertvector(v, bf16x2_t); return __builtin_bit_cast(unsigned, b); }
;     __device__ __forceinline__ void operator()(const f32x4 (&acc)[2][2][4][2], const pg8::Unit& u, int wr, int wc, int fr, int fq) const {
;     ...
;                 const int t = row & (SEQ - 1);
; #pragma unroll
;                 for (int bj = 0; bj < 2; ++bj) {
;                     f32x4 v0 = acc[ai][bj][m][0], v1 = acc[ai][bj][m][1];
;                     if (kind < 2) {
;                         v0 = v0 * rs * *(const f32x4*)(gp + 32 * bj); v1 = v1 * rs * *(const f32x4*)(gp + 32 * bj + 4);
;                         if (dorope) {
;                             const int pos = bj ? (t & 63) : (t >> 6);
;                             const f32x4 c0 = *(const f32x4*)(rp + pos * 16), c1 = *(const f32x4*)(rp + pos * 16 + 4);
;                             const f32x4 s0 = *(const f32x4*)(rp + 2048 + pos * 16), s1 = *(const f32x4*)(rp + 2048 + pos * 16 + 4);
;                             f32x4 o0, o1;
; #pragma unroll
;                             for (int i = 0; i < 4; ++i) { const float p0 = __uint_as_float((unsigned)__builtin_amdgcn_ds_bpermute(paddr, (int)__float_as_uint(v0[i]))) * s0[i], p1 = __uint_as_float((unsigned)__builtin_amdgcn_ds_bpermute(paddr, (int)__float_as_uint(v1[i]))) * s1[i];
;                                 o0[i] = v0[i] * c0[i] + (fq >= 2 ? p0 : -p0); o1[i] = v1[i] * c1[i] + (fq >= 2 ? p1 : -p1); }
;                             v0 = o0; v1 = o1;
;                         }
;                     }
;                     u32x4 w; w.x = pkbf(v0[0], v0[1]); w.y = pkbf(v0[2], v0[3]); w.z = pkbf(v1[0], v1[1]); w.w = pkbf(v1[2], v1[3]);
;                     *(u32x4*)(dst + (size_t)row * pitch + 32 * bj) = w;
	v_pk_mul_f32 v[214:215], v[206:207], v[214:215]
	v_pk_mul_f32 v[216:217], v[208:209], v[216:217]
	v_cndmask_b32_e64 v214, -v214, v214, s[6:7]
	v_cndmask_b32_e64 v215, -v215, v215, s[6:7]
	v_cndmask_b32_e64 v216, -v216, v216, s[6:7]
	v_cndmask_b32_e64 v217, -v217, v217, s[6:7]
	v_pk_fma_f32 v[68:69], v[68:69], v[198:199], v[214:215]
	v_pk_fma_f32 v[70:71], v[70:71], v[200:201], v[216:217]
	v_pk_mul_f32 v[218:219], v[210:211], v[218:219]
	v_pk_mul_f32 v[220:221], v[212:213], v[220:221]
	v_cndmask_b32_e64 v218, -v218, v218, s[6:7]
	v_cndmask_b32_e64 v219, -v219, v219, s[6:7]
	v_cndmask_b32_e64 v220, -v220, v220, s[6:7]
	v_cndmask_b32_e64 v221, -v221, v221, s[6:7]
	v_pk_fma_f32 v[64:65], v[64:65], v[202:203], v[218:219]
	v_pk_fma_f32 v[66:67], v[66:67], v[204:205], v[220:221]
	v_cvt_pk_bf16_f32 v68, v68, v69
	v_cvt_pk_bf16_f32 v69, v70, v71
	v_cvt_pk_bf16_f32 v70, v64, v65
	v_cvt_pk_bf16_f32 v71, v66, v67
	global_store_dwordx4 v142, v[68:71], s[36:37] offset:64
	v_lshl_add_u32 v221, s12, 8, v158
	v_add_u32_e32 v221, 128, v221
	v_and_b32_e32 v218, 0x1fc0, v221
	v_mov_b32_e32 v219, 0
	v_lshl_add_u64 v[214:215], v[138:139], 0, v[218:219]
	v_lshl_add_u64 v[216:217], v[140:141], 0, v[218:219]
	global_load_dwordx4 v[178:181], v[214:215], off
	global_load_dwordx4 v[182:185], v[214:215], off offset:16
	global_load_dwordx4 v[186:189], v[216:217], off
	global_load_dwordx4 v[190:193], v[216:217], off offset:16
	v_and_b32_e32 v218, 63, v221
	v_lshlrev_b32_e32 v218, 6, v218
	v_mov_b32_e32 v219, 0
	v_lshl_add_u64 v[214:215], v[138:139], 0, v[218:219]
	v_lshl_add_u64 v[216:217], v[140:141], 0, v[218:219]
	global_load_dwordx4 v[198:201], v[214:215], off
	global_load_dwordx4 v[202:205], v[214:215], off offset:16
	global_load_dwordx4 v[206:209], v[216:217], off
	global_load_dwordx4 v[210:213], v[216:217], off offset:16
	v_mul_f32_e32 v143, v61, v61
	v_mul_f32_e32 v144, v63, v63
	v_fmac_f32_e32 v143, v60, v60
	v_fmac_f32_e32 v144, v62, v62
	v_add_f32_e32 v142, v143, v144
	v_mul_f32_e32 v143, v57, v57
	v_mul_f32_e32 v144, v59, v59
	v_fmac_f32_e32 v143, v56, v56
	v_fmac_f32_e32 v144, v58, v58
	v_add_f32_e32 v143, v143, v144
	v_add_f32_e32 v142, v142, v143
	v_mul_f32_e32 v143, v53, v53
	v_mul_f32_e32 v144, v55, v55
	v_fmac_f32_e32 v143, v52, v52
	v_fmac_f32_e32 v144, v54, v54
	v_add_f32_e32 v143, v143, v144
	v_add_f32_e32 v142, v142, v143
	v_mul_f32_e32 v143, v49, v49
	v_mul_f32_e32 v144, v51, v51
	v_fmac_f32_e32 v143, v48, v48
	v_fmac_f32_e32 v144, v50, v50
	v_add_f32_e32 v143, v143, v144
	v_add_f32_e32 v142, v142, v143
	v_mov_b32_e32 v143, v142
	s_nop 1
	v_permlane16_swap_b32_e32 v142, v143
	v_add_f32_e32 v142, v142, v143
	v_mov_b32_e32 v143, v142
	s_nop 1
	v_permlane32_swap_b32_e32 v142, v143
	v_add_f32_e32 v142, v142, v143
	v_fmamk_f32 v144, v142, 0x3c800000, v153
	v_rsq_f32_e32 v144, v144
	s_nop 0
	v_pk_mul_f32 v[60:61], v[60:61], v[144:145] op_sel_hi:[1,0]
	v_pk_mul_f32 v[62:63], v[62:63], v[144:145] op_sel_hi:[1,0]
	v_pk_mul_f32 v[60:61], v[60:61], v[162:163]
	v_pk_mul_f32 v[62:63], v[62:63], v[164:165]
	v_pk_mul_f32 v[56:57], v[56:57], v[144:145] op_sel_hi:[1,0]
	v_pk_mul_f32 v[58:59], v[58:59], v[144:145] op_sel_hi:[1,0]
	v_pk_mul_f32 v[56:57], v[56:57], v[166:167]
	v_pk_mul_f32 v[58:59], v[58:59], v[168:169]
	v_pk_mul_f32 v[52:53], v[52:53], v[144:145] op_sel_hi:[1,0]
	v_pk_mul_f32 v[54:55], v[54:55], v[144:145] op_sel_hi:[1,0]
	v_pk_mul_f32 v[52:53], v[52:53], v[170:171]
	v_pk_mul_f32 v[54:55], v[54:55], v[172:173]
	v_pk_mul_f32 v[48:49], v[48:49], v[144:145] op_sel_hi:[1,0]
	v_pk_mul_f32 v[50:51], v[50:51], v[144:145] op_sel_hi:[1,0]
	v_pk_mul_f32 v[48:49], v[48:49], v[174:175]
	v_pk_mul_f32 v[50:51], v[50:51], v[176:177]
	ds_bpermute_b32 v214, v160, v60
	ds_bpermute_b32 v215, v160, v61
	ds_bpermute_b32 v216, v160, v62
	ds_bpermute_b32 v217, v160, v63
	ds_bpermute_b32 v218, v160, v56
	ds_bpermute_b32 v219, v160, v57
	ds_bpermute_b32 v220, v160, v58
	ds_bpermute_b32 v221, v160, v59
	s_waitcnt vmcnt(4)
	s_waitcnt lgkmcnt(0)
	v_pk_mul_f32 v[214:215], v[186:187], v[214:215]
	v_pk_mul_f32 v[216:217], v[188:189], v[216:217]
	v_cndmask_b32_e64 v214, -v214, v214, s[6:7]
	v_cndmask_b32_e64 v215, -v215, v215, s[6:7]
	v_cndmask_b32_e64 v216, -v216, v216, s[6:7]
	v_cndmask_b32_e64 v217, -v217, v217, s[6:7]
	v_pk_fma_f32 v[60:61], v[60:61], v[178:179], v[214:215]
	v_pk_fma_f32 v[62:63], v[62:63], v[180:181], v[216:217]
	v_pk_mul_f32 v[218:219], v[190:191], v[218:219]
	v_pk_mul_f32 v[220:221], v[192:193], v[220:221]
	v_cndmask_b32_e64 v218, -v218, v218, s[6:7]
	v_cndmask_b32_e64 v219, -v219, v219, s[6:7]
	v_cndmask_b32_e64 v220, -v220, v220, s[6:7]
	v_cndmask_b32_e64 v221, -v221, v221, s[6:7]
	v_pk_fma_f32 v[56:57], v[56:57], v[182:183], v[218:219]
	v_pk_fma_f32 v[58:59], v[58:59], v[184:185], v[220:221]
	v_lshl_add_u32 v142, s12, 8, v158
	v_add_u32_e32 v142, 128, v142
	v_lshl_add_u32 v142, v142, s13, v154
	v_cvt_pk_bf16_f32 v60, v60, v61
	v_cvt_pk_bf16_f32 v61, v62, v63
	v_cvt_pk_bf16_f32 v62, v56, v57
	v_cvt_pk_bf16_f32 v63, v58, v59
	global_store_dwordx4 v142, v[60:63], s[36:37]
	ds_bpermute_b32 v214, v160, v52
	ds_bpermute_b32 v215, v160, v53
	ds_bpermute_b32 v216, v160, v54
	ds_bpermute_b32 v217, v160, v55
	ds_bpermute_b32 v218, v160, v48
	ds_bpermute_b32 v219, v160, v49
	ds_bpermute_b32 v220, v160, v50
	ds_bpermute_b32 v221, v160, v51
	s_waitcnt vmcnt(1)
	s_waitcnt lgkmcnt(0)
; __device__ __forceinline__ unsigned pkbf(float lo, float hi) { f32x2_t v = {lo, hi}; bf16x2_t b = __builtin_convertvector(v, bf16x2_t); return __builtin_bit_cast(unsigned, b); }
;     __device__ __forceinline__ void operator()(const f32x4 (&acc)[2][2][4][2], const pg8::Unit& u, int wr, int wc, int fr, int fq) const {
;     ...
;                 const int t = row & (SEQ - 1);
; #pragma unroll
;                 for (int bj = 0; bj < 2; ++bj) {
;                     f32x4 v0 = acc[ai][bj][m][0], v1 = acc[ai][bj][m][1];
;                     if (kind < 2) {
;                         v0 = v0 * rs * *(const f32x4*)(gp + 32 * bj); v1 = v1 * rs * *(const f32x4*)(gp + 32 * bj + 4);
;                         if (dorope) {
;                             const int pos = bj ? (t & 63) : (t >> 6);
;                             const f32x4 c0 = *(const f32x4*)(rp + pos * 16), c1 = *(const f32x4*)(rp + pos * 16 + 4);
;                             const f32x4 s0 = *(const f32x4*)(rp + 2048 + pos * 16), s1 = *(const f32x4*)(rp + 2048 + pos * 16 + 4);
;                             f32x4 o0, o1;
; #pragma unroll
;                             for (int i = 0; i < 4; ++i) { const float p0 = __uint_as_float((unsigned)__builtin_amdgcn_ds_bpermute(paddr, (int)__float_as_uint(v0[i]))) * s0[i], p1 = __uint_as_float((unsigned)__builtin_amdgcn_ds_bpermute(paddr, (int)__float_as_uint(v1[i]))) * s1[i];
;                                 o0[i] = v0[i] * c0[i] + (fq >= 2 ? p0 : -p0); o1[i] = v1[i] * c1[i] + (fq >= 2 ? p1 : -p1); }
;                             v0 = o0; v1 = o1;
;                         }
;                     }
;                     u32x4 w; w.x = pkbf(v0[0], v0[1]); w.y = pkbf(v0[2], v0[3]); w.z = pkbf(v1[0], v1[1]); w.w = pkbf(v1[2], v1[3]);
;                     *(u32x4*)(dst + (size_t)row * pitch + 32 * bj) = w;
	v_pk_mul_f32 v[214:215], v[206:207], v[214:215]
	v_pk_mul_f32 v[216:217], v[208:209], v[216:217]
	v_cndmask_b32_e64 v214, -v214, v214, s[6:7]
	v_cndmask_b32_e64 v215, -v215, v215, s[6:7]
	v_cndmask_b32_e64 v216, -v216, v216, s[6:7]
	v_cndmask_b32_e64 v217, -v217, v217, s[6:7]
	v_pk_fma_f32 v[52:53], v[52:53], v[198:199], v[214:215]
	v_pk_fma_f32 v[54:55], v[54:55], v[200:201], v[216:217]
	v_pk_mul_f32 v[218:219], v[210:211], v[218:219]
	v_pk_mul_f32 v[220:221], v[212:213], v[220:221]
	v_cndmask_b32_e64 v218, -v218, v218, s[6:7]
	v_cndmask_b32_e64 v219, -v219, v219, s[6:7]
	v_cndmask_b32_e64 v220, -v220, v220, s[6:7]
	v_cndmask_b32_e64 v221, -v221, v221, s[6:7]
	v_pk_fma_f32 v[48:49], v[48:49], v[202:203], v[218:219]
	v_pk_fma_f32 v[50:51], v[50:51], v[204:205], v[220:221]
	v_cvt_pk_bf16_f32 v52, v52, v53
	v_cvt_pk_bf16_f32 v53, v54, v55
	v_cvt_pk_bf16_f32 v54, v48, v49
	v_cvt_pk_bf16_f32 v55, v50, v51
	global_store_dwordx4 v142, v[52:55], s[36:37] offset:64
	v_lshl_add_u32 v221, s12, 8, v158
	v_add_u32_e32 v221, 144, v221
	v_and_b32_e32 v218, 63, v221
	v_lshlrev_b32_e32 v218, 6, v218
	v_mov_b32_e32 v219, 0
	v_lshl_add_u64 v[214:215], v[138:139], 0, v[218:219]
	v_lshl_add_u64 v[216:217], v[140:141], 0, v[218:219]
	global_load_dwordx4 v[198:201], v[214:215], off
	global_load_dwordx4 v[202:205], v[214:215], off offset:16
	global_load_dwordx4 v[206:209], v[216:217], off
	global_load_dwordx4 v[210:213], v[216:217], off offset:16
	v_mul_f32_e32 v143, v45, v45
	v_mul_f32_e32 v144, v47, v47
	v_fmac_f32_e32 v143, v44, v44
	v_fmac_f32_e32 v144, v46, v46
	v_add_f32_e32 v142, v143, v144
	v_mul_f32_e32 v143, v41, v41
	v_mul_f32_e32 v144, v43, v43
	v_fmac_f32_e32 v143, v40, v40
	v_fmac_f32_e32 v144, v42, v42
	v_add_f32_e32 v143, v143, v144
	v_add_f32_e32 v142, v142, v143
	v_mul_f32_e32 v143, v37, v37
	v_mul_f32_e32 v144, v39, v39
	v_fmac_f32_e32 v143, v36, v36
	v_fmac_f32_e32 v144, v38, v38
	v_add_f32_e32 v143, v143, v144
	v_add_f32_e32 v142, v142, v143
	v_mul_f32_e32 v143, v33, v33
	v_mul_f32_e32 v144, v35, v35
	v_fmac_f32_e32 v143, v32, v32
	v_fmac_f32_e32 v144, v34, v34
	v_add_f32_e32 v143, v143, v144
	v_add_f32_e32 v142, v142, v143
	v_mov_b32_e32 v143, v142
	s_nop 1
	v_permlane16_swap_b32_e32 v142, v143
	v_add_f32_e32 v142, v142, v143
	v_mov_b32_e32 v143, v142
	s_nop 1
	v_permlane32_swap_b32_e32 v142, v143
	v_add_f32_e32 v142, v142, v143
	v_fmamk_f32 v144, v142, 0x3c800000, v153
	v_rsq_f32_e32 v144, v144
	s_nop 0
	v_pk_mul_f32 v[44:45], v[44:45], v[144:145] op_sel_hi:[1,0]
	v_pk_mul_f32 v[46:47], v[46:47], v[144:145] op_sel_hi:[1,0]
	v_pk_mul_f32 v[44:45], v[44:45], v[162:163]
	v_pk_mul_f32 v[46:47], v[46:47], v[164:165]
	v_pk_mul_f32 v[40:41], v[40:41], v[144:145] op_sel_hi:[1,0]
	v_pk_mul_f32 v[42:43], v[42:43], v[144:145] op_sel_hi:[1,0]
	v_pk_mul_f32 v[40:41], v[40:41], v[166:167]
	v_pk_mul_f32 v[42:43], v[42:43], v[168:169]
	v_pk_mul_f32 v[36:37], v[36:37], v[144:145] op_sel_hi:[1,0]
	v_pk_mul_f32 v[38:39], v[38:39], v[144:145] op_sel_hi:[1,0]
	v_pk_mul_f32 v[36:37], v[36:37], v[170:171]
	v_pk_mul_f32 v[38:39], v[38:39], v[172:173]
	v_pk_mul_f32 v[32:33], v[32:33], v[144:145] op_sel_hi:[1,0]
	v_pk_mul_f32 v[34:35], v[34:35], v[144:145] op_sel_hi:[1,0]
	v_pk_mul_f32 v[32:33], v[32:33], v[174:175]
	v_pk_mul_f32 v[34:35], v[34:35], v[176:177]
	ds_bpermute_b32 v214, v160, v44
	ds_bpermute_b32 v215, v160, v45
	ds_bpermute_b32 v216, v160, v46
	ds_bpermute_b32 v217, v160, v47
	ds_bpermute_b32 v218, v160, v40
	ds_bpermute_b32 v219, v160, v41
	ds_bpermute_b32 v220, v160, v42
	ds_bpermute_b32 v221, v160, v43
	s_waitcnt lgkmcnt(0)
	v_pk_mul_f32 v[214:215], v[186:187], v[214:215]
	v_pk_mul_f32 v[216:217], v[188:189], v[216:217]
	v_cndmask_b32_e64 v214, -v214, v214, s[6:7]
	v_cndmask_b32_e64 v215, -v215, v215, s[6:7]
	v_cndmask_b32_e64 v216, -v216, v216, s[6:7]
	v_cndmask_b32_e64 v217, -v217, v217, s[6:7]
	v_pk_fma_f32 v[44:45], v[44:45], v[178:179], v[214:215]
	v_pk_fma_f32 v[46:47], v[46:47], v[180:181], v[216:217]
	v_pk_mul_f32 v[218:219], v[190:191], v[218:219]
	v_pk_mul_f32 v[220:221], v[192:193], v[220:221]
	v_cndmask_b32_e64 v218, -v218, v218, s[6:7]
	v_cndmask_b32_e64 v219, -v219, v219, s[6:7]
	v_cndmask_b32_e64 v220, -v220, v220, s[6:7]
	v_cndmask_b32_e64 v221, -v221, v221, s[6:7]
	v_pk_fma_f32 v[40:41], v[40:41], v[182:183], v[218:219]
	v_pk_fma_f32 v[42:43], v[42:43], v[184:185], v[220:221]
	v_lshl_add_u32 v142, s12, 8, v158
	v_add_u32_e32 v142, 144, v142
	v_lshl_add_u32 v142, v142, s13, v154
	v_cvt_pk_bf16_f32 v44, v44, v45
	v_cvt_pk_bf16_f32 v45, v46, v47
	v_cvt_pk_bf16_f32 v46, v40, v41
	v_cvt_pk_bf16_f32 v47, v42, v43
	global_store_dwordx4 v142, v[44:47], s[36:37]
	ds_bpermute_b32 v214, v160, v36
	ds_bpermute_b32 v215, v160, v37
	ds_bpermute_b32 v216, v160, v38
	ds_bpermute_b32 v217, v160, v39
	ds_bpermute_b32 v218, v160, v32
	ds_bpermute_b32 v219, v160, v33
	ds_bpermute_b32 v220, v160, v34
	ds_bpermute_b32 v221, v160, v35
	s_waitcnt vmcnt(1)
	s_waitcnt lgkmcnt(0)
; __device__ __forceinline__ unsigned pkbf(float lo, float hi) { f32x2_t v = {lo, hi}; bf16x2_t b = __builtin_convertvector(v, bf16x2_t); return __builtin_bit_cast(unsigned, b); }
;     __device__ __forceinline__ void operator()(const f32x4 (&acc)[2][2][4][2], const pg8::Unit& u, int wr, int wc, int fr, int fq) const {
;     ...
;                 const int t = row & (SEQ - 1);
; #pragma unroll
;                 for (int bj = 0; bj < 2; ++bj) {
;                     f32x4 v0 = acc[ai][bj][m][0], v1 = acc[ai][bj][m][1];
;                     if (kind < 2) {
;                         v0 = v0 * rs * *(const f32x4*)(gp + 32 * bj); v1 = v1 * rs * *(const f32x4*)(gp + 32 * bj + 4);
;                         if (dorope) {
;                             const int pos = bj ? (t & 63) : (t >> 6);
;                             const f32x4 c0 = *(const f32x4*)(rp + pos * 16), c1 = *(const f32x4*)(rp + pos * 16 + 4);
;                             const f32x4 s0 = *(const f32x4*)(rp + 2048 + pos * 16), s1 = *(const f32x4*)(rp + 2048 + pos * 16 + 4);
;                             f32x4 o0, o1;
; #pragma unroll
;                             for (int i = 0; i < 4; ++i) { const float p0 = __uint_as_float((unsigned)__builtin_amdgcn_ds_bpermute(paddr, (int)__float_as_uint(v0[i]))) * s0[i], p1 = __uint_as_float((unsigned)__builtin_amdgcn_ds_bpermute(paddr, (int)__float_as_uint(v1[i]))) * s1[i];
;                                 o0[i] = v0[i] * c0[i] + (fq >= 2 ? p0 : -p0); o1[i] = v1[i] * c1[i] + (fq >= 2 ? p1 : -p1); }
;                             v0 = o0; v1 = o1;
;                         }
;                     }
;                     u32x4 w; w.x = pkbf(v0[0], v0[1]); w.y = pkbf(v0[2], v0[3]); w.z = pkbf(v1[0], v1[1]); w.w = pkbf(v1[2], v1[3]);
;                     *(u32x4*)(dst + (size_t)row * pitch + 32 * bj) = w;
	v_pk_mul_f32 v[214:215], v[206:207], v[214:215]
	v_pk_mul_f32 v[216:217], v[208:209], v[216:217]
	v_cndmask_b32_e64 v214, -v214, v214, s[6:7]
	v_cndmask_b32_e64 v215, -v215, v215, s[6:7]
	v_cndmask_b32_e64 v216, -v216, v216, s[6:7]
	v_cndmask_b32_e64 v217, -v217, v217, s[6:7]
	v_pk_fma_f32 v[36:37], v[36:37], v[198:199], v[214:215]
	v_pk_fma_f32 v[38:39], v[38:39], v[200:201], v[216:217]
	v_pk_mul_f32 v[218:219], v[210:211], v[218:219]
	v_pk_mul_f32 v[220:221], v[212:213], v[220:221]
	v_cndmask_b32_e64 v218, -v218, v218, s[6:7]
	v_cndmask_b32_e64 v219, -v219, v219, s[6:7]
	v_cndmask_b32_e64 v220, -v220, v220, s[6:7]
	v_cndmask_b32_e64 v221, -v221, v221, s[6:7]
	v_pk_fma_f32 v[32:33], v[32:33], v[202:203], v[218:219]
	v_pk_fma_f32 v[34:35], v[34:35], v[204:205], v[220:221]
	v_cvt_pk_bf16_f32 v36, v36, v37
	v_cvt_pk_bf16_f32 v37, v38, v39
	v_cvt_pk_bf16_f32 v38, v32, v33
	v_cvt_pk_bf16_f32 v39, v34, v35
	global_store_dwordx4 v142, v[36:39], s[36:37] offset:64
	v_lshl_add_u32 v221, s12, 8, v158
	v_add_u32_e32 v221, 160, v221
	v_and_b32_e32 v218, 63, v221
	v_lshlrev_b32_e32 v218, 6, v218
	v_mov_b32_e32 v219, 0
	v_lshl_add_u64 v[214:215], v[138:139], 0, v[218:219]
	v_lshl_add_u64 v[216:217], v[140:141], 0, v[218:219]
	global_load_dwordx4 v[198:201], v[214:215], off
	global_load_dwordx4 v[202:205], v[214:215], off offset:16
	global_load_dwordx4 v[206:209], v[216:217], off
	global_load_dwordx4 v[210:213], v[216:217], off offset:16
	v_mul_f32_e32 v143, v29, v29
	v_mul_f32_e32 v144, v31, v31
	v_fmac_f32_e32 v143, v28, v28
	v_fmac_f32_e32 v144, v30, v30
	v_add_f32_e32 v142, v143, v144
	v_mul_f32_e32 v143, v25, v25
	v_mul_f32_e32 v144, v27, v27
	v_fmac_f32_e32 v143, v24, v24
	v_fmac_f32_e32 v144, v26, v26
	v_add_f32_e32 v143, v143, v144
	v_add_f32_e32 v142, v142, v143
	v_mul_f32_e32 v143, v21, v21
	v_mul_f32_e32 v144, v23, v23
	v_fmac_f32_e32 v143, v20, v20
	v_fmac_f32_e32 v144, v22, v22
	v_add_f32_e32 v143, v143, v144
	v_add_f32_e32 v142, v142, v143
	v_mul_f32_e32 v143, v17, v17
	v_mul_f32_e32 v144, v19, v19
	v_fmac_f32_e32 v143, v16, v16
	v_fmac_f32_e32 v144, v18, v18
	v_add_f32_e32 v143, v143, v144
	v_add_f32_e32 v142, v142, v143
	v_mov_b32_e32 v143, v142
	s_nop 1
	v_permlane16_swap_b32_e32 v142, v143
	v_add_f32_e32 v142, v142, v143
	v_mov_b32_e32 v143, v142
	s_nop 1
	v_permlane32_swap_b32_e32 v142, v143
	v_add_f32_e32 v142, v142, v143
	v_fmamk_f32 v144, v142, 0x3c800000, v153
	v_rsq_f32_e32 v144, v144
	s_nop 0
	v_pk_mul_f32 v[28:29], v[28:29], v[144:145] op_sel_hi:[1,0]
	v_pk_mul_f32 v[30:31], v[30:31], v[144:145] op_sel_hi:[1,0]
	v_pk_mul_f32 v[28:29], v[28:29], v[162:163]
	v_pk_mul_f32 v[30:31], v[30:31], v[164:165]
	v_pk_mul_f32 v[24:25], v[24:25], v[144:145] op_sel_hi:[1,0]
	v_pk_mul_f32 v[26:27], v[26:27], v[144:145] op_sel_hi:[1,0]
	v_pk_mul_f32 v[24:25], v[24:25], v[166:167]
	v_pk_mul_f32 v[26:27], v[26:27], v[168:169]
	v_pk_mul_f32 v[20:21], v[20:21], v[144:145] op_sel_hi:[1,0]
	v_pk_mul_f32 v[22:23], v[22:23], v[144:145] op_sel_hi:[1,0]
	v_pk_mul_f32 v[20:21], v[20:21], v[170:171]
	v_pk_mul_f32 v[22:23], v[22:23], v[172:173]
	v_pk_mul_f32 v[16:17], v[16:17], v[144:145] op_sel_hi:[1,0]
	v_pk_mul_f32 v[18:19], v[18:19], v[144:145] op_sel_hi:[1,0]
	v_pk_mul_f32 v[16:17], v[16:17], v[174:175]
	v_pk_mul_f32 v[18:19], v[18:19], v[176:177]
	ds_bpermute_b32 v214, v160, v28
	ds_bpermute_b32 v215, v160, v29
	ds_bpermute_b32 v216, v160, v30
	ds_bpermute_b32 v217, v160, v31
	ds_bpermute_b32 v218, v160, v24
	ds_bpermute_b32 v219, v160, v25
	ds_bpermute_b32 v220, v160, v26
	ds_bpermute_b32 v221, v160, v27
	s_waitcnt lgkmcnt(0)
	v_pk_mul_f32 v[214:215], v[186:187], v[214:215]
	v_pk_mul_f32 v[216:217], v[188:189], v[216:217]
	v_cndmask_b32_e64 v214, -v214, v214, s[6:7]
	v_cndmask_b32_e64 v215, -v215, v215, s[6:7]
	v_cndmask_b32_e64 v216, -v216, v216, s[6:7]
	v_cndmask_b32_e64 v217, -v217, v217, s[6:7]
	v_pk_fma_f32 v[28:29], v[28:29], v[178:179], v[214:215]
	v_pk_fma_f32 v[30:31], v[30:31], v[180:181], v[216:217]
	v_pk_mul_f32 v[218:219], v[190:191], v[218:219]
	v_pk_mul_f32 v[220:221], v[192:193], v[220:221]
	v_cndmask_b32_e64 v218, -v218, v218, s[6:7]
	v_cndmask_b32_e64 v219, -v219, v219, s[6:7]
	v_cndmask_b32_e64 v220, -v220, v220, s[6:7]
	v_cndmask_b32_e64 v221, -v221, v221, s[6:7]
	v_pk_fma_f32 v[24:25], v[24:25], v[182:183], v[218:219]
	v_pk_fma_f32 v[26:27], v[26:27], v[184:185], v[220:221]
	v_lshl_add_u32 v142, s12, 8, v158
	v_add_u32_e32 v142, 160, v142
	v_lshl_add_u32 v142, v142, s13, v154
	v_cvt_pk_bf16_f32 v28, v28, v29
	v_cvt_pk_bf16_f32 v29, v30, v31
	v_cvt_pk_bf16_f32 v30, v24, v25
	v_cvt_pk_bf16_f32 v31, v26, v27
	global_store_dwordx4 v142, v[28:31], s[36:37]
	ds_bpermute_b32 v214, v160, v20
	ds_bpermute_b32 v215, v160, v21
	ds_bpermute_b32 v216, v160, v22
	ds_bpermute_b32 v217, v160, v23
	ds_bpermute_b32 v218, v160, v16
	ds_bpermute_b32 v219, v160, v17
	ds_bpermute_b32 v220, v160, v18
	ds_bpermute_b32 v221, v160, v19
	s_waitcnt vmcnt(1)
	s_waitcnt lgkmcnt(0)
; __device__ __forceinline__ unsigned pkbf(float lo, float hi) { f32x2_t v = {lo, hi}; bf16x2_t b = __builtin_convertvector(v, bf16x2_t); return __builtin_bit_cast(unsigned, b); }
;     __device__ __forceinline__ void operator()(const f32x4 (&acc)[2][2][4][2], const pg8::Unit& u, int wr, int wc, int fr, int fq) const {
;     ...
;                 const int t = row & (SEQ - 1);
; #pragma unroll
;                 for (int bj = 0; bj < 2; ++bj) {
;                     f32x4 v0 = acc[ai][bj][m][0], v1 = acc[ai][bj][m][1];
;                     if (kind < 2) {
;                         v0 = v0 * rs * *(const f32x4*)(gp + 32 * bj); v1 = v1 * rs * *(const f32x4*)(gp + 32 * bj + 4);
;                         if (dorope) {
;                             const int pos = bj ? (t & 63) : (t >> 6);
;                             const f32x4 c0 = *(const f32x4*)(rp + pos * 16), c1 = *(const f32x4*)(rp + pos * 16 + 4);
;                             const f32x4 s0 = *(const f32x4*)(rp + 2048 + pos * 16), s1 = *(const f32x4*)(rp + 2048 + pos * 16 + 4);
;                             f32x4 o0, o1;
; #pragma unroll
;                             for (int i = 0; i < 4; ++i) { const float p0 = __uint_as_float((unsigned)__builtin_amdgcn_ds_bpermute(paddr, (int)__float_as_uint(v0[i]))) * s0[i], p1 = __uint_as_float((unsigned)__builtin_amdgcn_ds_bpermute(paddr, (int)__float_as_uint(v1[i]))) * s1[i];
;                                 o0[i] = v0[i] * c0[i] + (fq >= 2 ? p0 : -p0); o1[i] = v1[i] * c1[i] + (fq >= 2 ? p1 : -p1); }
;                             v0 = o0; v1 = o1;
;                         }
;                     }
;                     u32x4 w; w.x = pkbf(v0[0], v0[1]); w.y = pkbf(v0[2], v0[3]); w.z = pkbf(v1[0], v1[1]); w.w = pkbf(v1[2], v1[3]);
;                     *(u32x4*)(dst + (size_t)row * pitch + 32 * bj) = w;
;                 }
;                 asm volatile("" ::: "memory");
;             }
;     }
	v_pk_mul_f32 v[214:215], v[206:207], v[214:215]
	v_pk_mul_f32 v[216:217], v[208:209], v[216:217]
	v_cndmask_b32_e64 v214, -v214, v214, s[6:7]
	v_cndmask_b32_e64 v215, -v215, v215, s[6:7]
	v_cndmask_b32_e64 v216, -v216, v216, s[6:7]
	v_cndmask_b32_e64 v217, -v217, v217, s[6:7]
	v_pk_fma_f32 v[20:21], v[20:21], v[198:199], v[214:215]
	v_pk_fma_f32 v[22:23], v[22:23], v[200:201], v[216:217]
	v_pk_mul_f32 v[218:219], v[210:211], v[218:219]
	v_pk_mul_f32 v[220:221], v[212:213], v[220:221]
	v_cndmask_b32_e64 v218, -v218, v218, s[6:7]
	v_cndmask_b32_e64 v219, -v219, v219, s[6:7]
	v_cndmask_b32_e64 v220, -v220, v220, s[6:7]
	v_cndmask_b32_e64 v221, -v221, v221, s[6:7]
	v_pk_fma_f32 v[16:17], v[16:17], v[202:203], v[218:219]
	v_pk_fma_f32 v[18:19], v[18:19], v[204:205], v[220:221]
	v_cvt_pk_bf16_f32 v20, v20, v21
	v_cvt_pk_bf16_f32 v21, v22, v23
	v_cvt_pk_bf16_f32 v22, v16, v17
	v_cvt_pk_bf16_f32 v23, v18, v19
	global_store_dwordx4 v142, v[20:23], s[36:37] offset:64
	v_lshl_add_u32 v221, s12, 8, v158
	v_add_u32_e32 v221, 176, v221
	v_and_b32_e32 v218, 63, v221
	v_lshlrev_b32_e32 v218, 6, v218
	v_mov_b32_e32 v219, 0
	v_lshl_add_u64 v[214:215], v[138:139], 0, v[218:219]
	v_lshl_add_u64 v[216:217], v[140:141], 0, v[218:219]
	global_load_dwordx4 v[198:201], v[214:215], off
	global_load_dwordx4 v[202:205], v[214:215], off offset:16
	global_load_dwordx4 v[206:209], v[216:217], off
	global_load_dwordx4 v[210:213], v[216:217], off offset:16
	v_mul_f32_e32 v143, v13, v13
	v_mul_f32_e32 v144, v15, v15
	v_fmac_f32_e32 v143, v12, v12
	v_fmac_f32_e32 v144, v14, v14
	v_add_f32_e32 v142, v143, v144
	v_mul_f32_e32 v143, v9, v9
	v_mul_f32_e32 v144, v11, v11
	v_fmac_f32_e32 v143, v8, v8
	v_fmac_f32_e32 v144, v10, v10
	v_add_f32_e32 v143, v143, v144
	v_add_f32_e32 v142, v142, v143
	v_mul_f32_e32 v143, v5, v5
	v_mul_f32_e32 v144, v7, v7
	v_fmac_f32_e32 v143, v4, v4
	v_fmac_f32_e32 v144, v6, v6
	v_add_f32_e32 v143, v143, v144
	v_add_f32_e32 v142, v142, v143
	v_mul_f32_e32 v143, v1, v1
	v_mul_f32_e32 v144, v3, v3
	v_fmac_f32_e32 v143, v0, v0
	v_fmac_f32_e32 v144, v2, v2
	v_add_f32_e32 v143, v143, v144
	v_add_f32_e32 v142, v142, v143
	v_mov_b32_e32 v143, v142
	s_nop 1
	v_permlane16_swap_b32_e32 v142, v143
	v_add_f32_e32 v142, v142, v143
	v_mov_b32_e32 v143, v142
	s_nop 1
	v_permlane32_swap_b32_e32 v142, v143
	v_add_f32_e32 v142, v142, v143
	v_fmamk_f32 v144, v142, 0x3c800000, v153
	v_rsq_f32_e32 v144, v144
	s_nop 0
	v_pk_mul_f32 v[12:13], v[12:13], v[144:145] op_sel_hi:[1,0]
	v_pk_mul_f32 v[14:15], v[14:15], v[144:145] op_sel_hi:[1,0]
	v_pk_mul_f32 v[12:13], v[12:13], v[162:163]
	v_pk_mul_f32 v[14:15], v[14:15], v[164:165]
	v_pk_mul_f32 v[8:9], v[8:9], v[144:145] op_sel_hi:[1,0]
	v_pk_mul_f32 v[10:11], v[10:11], v[144:145] op_sel_hi:[1,0]
	v_pk_mul_f32 v[8:9], v[8:9], v[166:167]
	v_pk_mul_f32 v[10:11], v[10:11], v[168:169]
	v_pk_mul_f32 v[4:5], v[4:5], v[144:145] op_sel_hi:[1,0]
	v_pk_mul_f32 v[6:7], v[6:7], v[144:145] op_sel_hi:[1,0]
	v_pk_mul_f32 v[4:5], v[4:5], v[170:171]
	v_pk_mul_f32 v[6:7], v[6:7], v[172:173]
	v_pk_mul_f32 v[0:1], v[0:1], v[144:145] op_sel_hi:[1,0]
	v_pk_mul_f32 v[2:3], v[2:3], v[144:145] op_sel_hi:[1,0]
	v_pk_mul_f32 v[0:1], v[0:1], v[174:175]
	v_pk_mul_f32 v[2:3], v[2:3], v[176:177]
	ds_bpermute_b32 v214, v160, v12
	ds_bpermute_b32 v215, v160, v13
	ds_bpermute_b32 v216, v160, v14
	ds_bpermute_b32 v217, v160, v15
	ds_bpermute_b32 v218, v160, v8
	ds_bpermute_b32 v219, v160, v9
	ds_bpermute_b32 v220, v160, v10
	ds_bpermute_b32 v221, v160, v11
	s_waitcnt lgkmcnt(0)
	v_pk_mul_f32 v[214:215], v[186:187], v[214:215]
	v_pk_mul_f32 v[216:217], v[188:189], v[216:217]
	v_cndmask_b32_e64 v214, -v214, v214, s[6:7]
	v_cndmask_b32_e64 v215, -v215, v215, s[6:7]
	v_cndmask_b32_e64 v216, -v216, v216, s[6:7]
	v_cndmask_b32_e64 v217, -v217, v217, s[6:7]
	v_pk_fma_f32 v[12:13], v[12:13], v[178:179], v[214:215]
	v_pk_fma_f32 v[14:15], v[14:15], v[180:181], v[216:217]
	v_pk_mul_f32 v[218:219], v[190:191], v[218:219]
	v_pk_mul_f32 v[220:221], v[192:193], v[220:221]
	v_cndmask_b32_e64 v218, -v218, v218, s[6:7]
	v_cndmask_b32_e64 v219, -v219, v219, s[6:7]
	v_cndmask_b32_e64 v220, -v220, v220, s[6:7]
	v_cndmask_b32_e64 v221, -v221, v221, s[6:7]
	v_pk_fma_f32 v[8:9], v[8:9], v[182:183], v[218:219]
	v_pk_fma_f32 v[10:11], v[10:11], v[184:185], v[220:221]
	v_lshl_add_u32 v142, s12, 8, v158
	v_add_u32_e32 v142, 176, v142
	v_lshl_add_u32 v142, v142, s13, v154
	v_cvt_pk_bf16_f32 v12, v12, v13
	v_cvt_pk_bf16_f32 v13, v14, v15
	v_cvt_pk_bf16_f32 v14, v8, v9
	v_cvt_pk_bf16_f32 v15, v10, v11
	global_store_dwordx4 v142, v[12:15], s[36:37]
	ds_bpermute_b32 v214, v160, v4
	ds_bpermute_b32 v215, v160, v5
	ds_bpermute_b32 v216, v160, v6
	ds_bpermute_b32 v217, v160, v7
	ds_bpermute_b32 v218, v160, v0
	ds_bpermute_b32 v219, v160, v1
	ds_bpermute_b32 v220, v160, v2
	ds_bpermute_b32 v221, v160, v3
	s_waitcnt vmcnt(1)
	s_waitcnt lgkmcnt(0)
	v_pk_mul_f32 v[214:215], v[206:207], v[214:215]
	v_pk_mul_f32 v[216:217], v[208:209], v[216:217]
	v_cndmask_b32_e64 v214, -v214, v214, s[6:7]
	v_cndmask_b32_e64 v215, -v215, v215, s[6:7]
	v_cndmask_b32_e64 v216, -v216, v216, s[6:7]
	v_cndmask_b32_e64 v217, -v217, v217, s[6:7]
	v_pk_fma_f32 v[4:5], v[4:5], v[198:199], v[214:215]
	v_pk_fma_f32 v[6:7], v[6:7], v[200:201], v[216:217]
	v_pk_mul_f32 v[218:219], v[210:211], v[218:219]
	v_pk_mul_f32 v[220:221], v[212:213], v[220:221]
	v_cndmask_b32_e64 v218, -v218, v218, s[6:7]
	v_cndmask_b32_e64 v219, -v219, v219, s[6:7]
	v_cndmask_b32_e64 v220, -v220, v220, s[6:7]
	v_cndmask_b32_e64 v221, -v221, v221, s[6:7]
	v_pk_fma_f32 v[0:1], v[0:1], v[202:203], v[218:219]
	v_pk_fma_f32 v[2:3], v[2:3], v[204:205], v[220:221]
	v_cvt_pk_bf16_f32 v4, v4, v5
	v_cvt_pk_bf16_f32 v5, v6, v7
	v_cvt_pk_bf16_f32 v6, v0, v1
	v_cvt_pk_bf16_f32 v7, v2, v3
	global_store_dwordx4 v142, v[4:7], s[36:37] offset:64
	s_branch .Lqkv_join
.Lqkv_join:
	s_andn2_b64 vcc, exec, s[8:9]
	s_mov_b64 s[8:9], -1
	s_cbranch_vccnz .LBB0_209
	s_andn2_b64 vcc, exec, s[14:15]
	s_cbranch_vccnz .LBB0_208
	s_barrier
	s_branch .LBB0_208

; __device__ __forceinline__ unsigned pkbf(float lo, float hi) { f32x2_t v = {lo, hi}; bf16x2_t b = __builtin_convertvector(v, bf16x2_t); return __builtin_bit_cast(unsigned, b); }
;     __device__ __forceinline__ void operator()(const f32x4 (&acc)[2][2][4][2], const pg8::Unit& u, int wr, int wc, int fr, int fq) const {
;         const int row0 = u.pm * 256 + wr * 64 + fr, col0 = u.pn * 256 + wc * 32 + 8 * fq;
; #pragma unroll
;         for (int ai = 0; ai < 2; ++ai)
; #pragma unroll
;             for (int m = 0; m < 4; ++m) { bf16_t* rowp = O + (size_t)(row0 + ai * 128 + m * 16) * ldc + col0;
; #pragma unroll
;                 for (int bj = 0; bj < 2; ++bj) { f32x4 v0 = acc[ai][bj][m][0], v1 = acc[ai][bj][m][1];
; #pragma unroll
;                     for (int i = 0; i < 4; ++i) { float a = fmaxf(v0[i], 0.f), b = fmaxf(v1[i], 0.f); v0[i] = a * a; v1[i] = b * b; }
;                     u32x4 w; w.x = pkbf(v0[0], v0[1]); w.y = pkbf(v0[2], v0[3]); w.z = pkbf(v1[0], v1[1]); w.w = pkbf(v1[2], v1[3]);
;                     *(u32x4*)(rowp + bj * 128) = w; } }
.LBB0_806:
	v_lshl_add_u32 v140, s24, 8, v136
	v_lshl_or_b32 v134, s22, 8, v138
	v_ashrrev_i32_e32 v141, 31, v140
	v_readlane_b32 s26, v241, 37
	v_ashrrev_i32_e32 v135, 31, v134
	v_lshlrev_b64 v[142:143], 13, v[140:141]
	v_readlane_b32 s27, v241, 38
	v_lshl_add_u64 v[142:143], s[26:27], 0, v[142:143]
	v_lshlrev_b64 v[144:145], 1, v[134:135]
	v_max_f32_e32 v120, 0, v120
	v_max_f32_e32 v121, 0, v121
	v_lshl_add_u64 v[134:135], v[142:143], 0, v[144:145]
	v_pk_mul_f32 v[142:143], v[120:121], v[120:121]
	v_max_f32_e32 v122, 0, v122
	v_max_f32_e32 v124, 0, v124
	v_max_f32_e32 v125, 0, v125
	v_max_f32_e32 v120, 0, v126
	v_max_f32_e32 v121, 0, v127
	v_max_f32_e32 v123, 0, v123
	v_pk_mul_f32 v[124:125], v[124:125], v[124:125]
	v_pk_mul_f32 v[126:127], v[120:121], v[120:121]
	v_pk_mul_f32 v[146:147], v[122:123], v[122:123]
	v_cvt_pk_bf16_f32 v120, v124, v125
	v_cvt_pk_bf16_f32 v121, v126, v127
	v_cvt_pk_bf16_f32 v122, v142, v143
	v_cvt_pk_bf16_f32 v123, v146, v147
	v_max_f32_e32 v112, 0, v112
	v_max_f32_e32 v113, 0, v113
	global_store_dwordx4 v[134:135], v[120:123], off
	s_nop 1
	v_pk_mul_f32 v[120:121], v[112:113], v[112:113]
	v_max_f32_e32 v114, 0, v114
	v_max_f32_e32 v116, 0, v116
	v_max_f32_e32 v117, 0, v117
	v_max_f32_e32 v112, 0, v118
	v_max_f32_e32 v113, 0, v119
	v_max_f32_e32 v115, 0, v115
	v_pk_mul_f32 v[116:117], v[116:117], v[116:117]
	v_pk_mul_f32 v[118:119], v[112:113], v[112:113]
	v_pk_mul_f32 v[122:123], v[114:115], v[114:115]
	v_cvt_pk_bf16_f32 v112, v116, v117
	v_cvt_pk_bf16_f32 v113, v118, v119
	v_cvt_pk_bf16_f32 v114, v120, v121
	v_cvt_pk_bf16_f32 v115, v122, v123
	v_max_f32_e32 v104, 0, v104
	v_max_f32_e32 v105, 0, v105
	global_store_dwordx4 v[134:135], v[112:115], off offset:256
	s_nop 1
	v_or_b32_e32 v112, 16, v140
	v_pk_mul_f32 v[114:115], v[104:105], v[104:105]
	v_ashrrev_i32_e32 v113, 31, v112
	v_max_f32_e32 v106, 0, v106
	v_lshlrev_b64 v[112:113], 13, v[112:113]
	v_max_f32_e32 v108, 0, v108
	v_max_f32_e32 v109, 0, v109
	v_max_f32_e32 v104, 0, v110
	v_max_f32_e32 v105, 0, v111
	v_max_f32_e32 v107, 0, v107
	v_lshl_add_u64 v[112:113], s[26:27], 0, v[112:113]
	v_pk_mul_f32 v[108:109], v[108:109], v[108:109]
	v_pk_mul_f32 v[110:111], v[104:105], v[104:105]
	v_pk_mul_f32 v[116:117], v[106:107], v[106:107]
	v_lshl_add_u64 v[112:113], v[112:113], 0, v[144:145]
	v_cvt_pk_bf16_f32 v104, v108, v109
	v_cvt_pk_bf16_f32 v105, v110, v111
	v_cvt_pk_bf16_f32 v106, v114, v115
	v_cvt_pk_bf16_f32 v107, v116, v117
	v_max_f32_e32 v96, 0, v96
	v_max_f32_e32 v97, 0, v97
	global_store_dwordx4 v[112:113], v[104:107], off
	s_nop 1
	v_pk_mul_f32 v[104:105], v[96:97], v[96:97]
	v_max_f32_e32 v98, 0, v98
	v_max_f32_e32 v100, 0, v100
	v_max_f32_e32 v101, 0, v101
	v_max_f32_e32 v96, 0, v102
	v_max_f32_e32 v97, 0, v103
	v_max_f32_e32 v99, 0, v99
	v_pk_mul_f32 v[100:101], v[100:101], v[100:101]
	v_pk_mul_f32 v[102:103], v[96:97], v[96:97]
	v_pk_mul_f32 v[106:107], v[98:99], v[98:99]
	v_cvt_pk_bf16_f32 v96, v100, v101
	v_cvt_pk_bf16_f32 v97, v102, v103
	v_cvt_pk_bf16_f32 v98, v104, v105
	v_cvt_pk_bf16_f32 v99, v106, v107
	v_max_f32_e32 v88, 0, v88
	v_max_f32_e32 v89, 0, v89
	global_store_dwordx4 v[112:113], v[96:99], off offset:256
	s_nop 1
	v_or_b32_e32 v96, 32, v140
	v_pk_mul_f32 v[98:99], v[88:89], v[88:89]
	v_ashrrev_i32_e32 v97, 31, v96
	v_max_f32_e32 v90, 0, v90
	v_lshlrev_b64 v[96:97], 13, v[96:97]
	v_max_f32_e32 v92, 0, v92
	v_max_f32_e32 v93, 0, v93
	v_max_f32_e32 v88, 0, v94
	v_max_f32_e32 v89, 0, v95
	v_max_f32_e32 v91, 0, v91
	v_lshl_add_u64 v[96:97], s[26:27], 0, v[96:97]
	v_pk_mul_f32 v[92:93], v[92:93], v[92:93]
	v_pk_mul_f32 v[94:95], v[88:89], v[88:89]
	v_pk_mul_f32 v[100:101], v[90:91], v[90:91]
	v_lshl_add_u64 v[96:97], v[96:97], 0, v[144:145]
	v_cvt_pk_bf16_f32 v88, v92, v93
	v_cvt_pk_bf16_f32 v89, v94, v95
	v_cvt_pk_bf16_f32 v90, v98, v99
	v_cvt_pk_bf16_f32 v91, v100, v101
	v_max_f32_e32 v80, 0, v80
	v_max_f32_e32 v81, 0, v81
	global_store_dwordx4 v[96:97], v[88:91], off
	s_nop 1
	v_pk_mul_f32 v[88:89], v[80:81], v[80:81]
	v_max_f32_e32 v82, 0, v82
	v_max_f32_e32 v84, 0, v84
	v_max_f32_e32 v85, 0, v85
	v_max_f32_e32 v80, 0, v86
	v_max_f32_e32 v81, 0, v87
	v_max_f32_e32 v83, 0, v83
	v_pk_mul_f32 v[84:85], v[84:85], v[84:85]
	v_pk_mul_f32 v[86:87], v[80:81], v[80:81]
	v_pk_mul_f32 v[90:91], v[82:83], v[82:83]
	v_cvt_pk_bf16_f32 v80, v84, v85
	v_cvt_pk_bf16_f32 v81, v86, v87
	v_cvt_pk_bf16_f32 v82, v88, v89
	v_cvt_pk_bf16_f32 v83, v90, v91
	v_max_f32_e32 v72, 0, v72
	v_max_f32_e32 v73, 0, v73
	global_store_dwordx4 v[96:97], v[80:83], off offset:256
	s_nop 1
	v_or_b32_e32 v80, 48, v140
	v_pk_mul_f32 v[82:83], v[72:73], v[72:73]
	v_ashrrev_i32_e32 v81, 31, v80
	v_max_f32_e32 v74, 0, v74
	v_lshlrev_b64 v[80:81], 13, v[80:81]
	v_max_f32_e32 v76, 0, v76
	v_max_f32_e32 v77, 0, v77
	v_max_f32_e32 v72, 0, v78
	v_max_f32_e32 v73, 0, v79
	v_max_f32_e32 v75, 0, v75
	v_lshl_add_u64 v[80:81], s[26:27], 0, v[80:81]
	v_pk_mul_f32 v[76:77], v[76:77], v[76:77]
	v_pk_mul_f32 v[78:79], v[72:73], v[72:73]
	v_pk_mul_f32 v[84:85], v[74:75], v[74:75]
	v_lshl_add_u64 v[80:81], v[80:81], 0, v[144:145]
	v_cvt_pk_bf16_f32 v72, v76, v77
	v_cvt_pk_bf16_f32 v73, v78, v79
	v_cvt_pk_bf16_f32 v74, v82, v83
	v_cvt_pk_bf16_f32 v75, v84, v85
	v_max_f32_e32 v64, 0, v64
	v_max_f32_e32 v65, 0, v65
	global_store_dwordx4 v[80:81], v[72:75], off
	s_nop 1
	v_pk_mul_f32 v[72:73], v[64:65], v[64:65]
	v_max_f32_e32 v66, 0, v66
	v_max_f32_e32 v68, 0, v68
	v_max_f32_e32 v69, 0, v69
	v_max_f32_e32 v64, 0, v70
	v_max_f32_e32 v65, 0, v71
	v_max_f32_e32 v67, 0, v67
	v_pk_mul_f32 v[68:69], v[68:69], v[68:69]
	v_pk_mul_f32 v[70:71], v[64:65], v[64:65]
	v_pk_mul_f32 v[74:75], v[66:67], v[66:67]
; __device__ __forceinline__ unsigned pkbf(float lo, float hi) { f32x2_t v = {lo, hi}; bf16x2_t b = __builtin_convertvector(v, bf16x2_t); return __builtin_bit_cast(unsigned, b); }
;     __device__ __forceinline__ void operator()(const f32x4 (&acc)[2][2][4][2], const pg8::Unit& u, int wr, int wc, int fr, int fq) const {
;         const int row0 = u.pm * 256 + wr * 64 + fr, col0 = u.pn * 256 + wc * 32 + 8 * fq;
; #pragma unroll
;         for (int ai = 0; ai < 2; ++ai)
; #pragma unroll
;             for (int m = 0; m < 4; ++m) { bf16_t* rowp = O + (size_t)(row0 + ai * 128 + m * 16) * ldc + col0;
; #pragma unroll
;                 for (int bj = 0; bj < 2; ++bj) { f32x4 v0 = acc[ai][bj][m][0], v1 = acc[ai][bj][m][1];
; #pragma unroll
;                     for (int i = 0; i < 4; ++i) { float a = fmaxf(v0[i], 0.f), b = fmaxf(v1[i], 0.f); v0[i] = a * a; v1[i] = b * b; }
;                     u32x4 w; w.x = pkbf(v0[0], v0[1]); w.y = pkbf(v0[2], v0[3]); w.z = pkbf(v1[0], v1[1]); w.w = pkbf(v1[2], v1[3]);
;                     *(u32x4*)(rowp + bj * 128) = w; } }
	v_cvt_pk_bf16_f32 v64, v68, v69
	v_cvt_pk_bf16_f32 v65, v70, v71
	v_cvt_pk_bf16_f32 v66, v72, v73
	v_cvt_pk_bf16_f32 v67, v74, v75
	v_max_f32_e32 v56, 0, v56
	v_max_f32_e32 v57, 0, v57
	global_store_dwordx4 v[80:81], v[64:67], off offset:256
	s_nop 1
	v_pk_mul_f32 v[66:67], v[56:57], v[56:57]
	v_max_f32_e32 v60, 0, v60
	v_max_f32_e32 v61, 0, v61
	v_max_f32_e32 v58, 0, v58
	v_pk_mul_f32 v[60:61], v[60:61], v[60:61]
	v_max_f32_e32 v56, 0, v62
	v_max_f32_e32 v57, 0, v63
	v_max_f32_e32 v59, 0, v59
	s_mov_b32 s13, 0x100000
	v_pk_mul_f32 v[62:63], v[56:57], v[56:57]
	v_pk_mul_f32 v[68:69], v[58:59], v[58:59]
	v_cvt_pk_bf16_f32 v56, v60, v61
	v_add_co_u32_e32 v60, vcc, s13, v134
	v_cvt_pk_bf16_f32 v57, v62, v63
	v_cvt_pk_bf16_f32 v58, v66, v67
	v_cvt_pk_bf16_f32 v59, v68, v69
	v_addc_co_u32_e32 v61, vcc, 0, v135, vcc
	v_max_f32_e32 v48, 0, v48
	v_max_f32_e32 v49, 0, v49
	global_store_dwordx4 v[60:61], v[56:59], off
	s_nop 1
	v_pk_mul_f32 v[56:57], v[48:49], v[48:49]
	v_max_f32_e32 v50, 0, v50
	v_max_f32_e32 v52, 0, v52
	v_max_f32_e32 v53, 0, v53
	v_max_f32_e32 v48, 0, v54
	v_max_f32_e32 v49, 0, v55
	v_max_f32_e32 v51, 0, v51
	v_pk_mul_f32 v[52:53], v[52:53], v[52:53]
	v_pk_mul_f32 v[54:55], v[48:49], v[48:49]
	v_pk_mul_f32 v[58:59], v[50:51], v[50:51]
	v_lshl_add_u64 v[64:65], v[134:135], 0, s[80:81]
	v_cvt_pk_bf16_f32 v48, v52, v53
	v_cvt_pk_bf16_f32 v49, v54, v55
	v_cvt_pk_bf16_f32 v50, v56, v57
	v_cvt_pk_bf16_f32 v51, v58, v59
	v_max_f32_e32 v40, 0, v40
	v_max_f32_e32 v41, 0, v41
	global_store_dwordx4 v[64:65], v[48:51], off offset:256
	s_nop 1
	v_pk_mul_f32 v[50:51], v[40:41], v[40:41]
	v_max_f32_e32 v44, 0, v44
	v_max_f32_e32 v45, 0, v45
	v_max_f32_e32 v42, 0, v42
	v_pk_mul_f32 v[44:45], v[44:45], v[44:45]
	v_max_f32_e32 v40, 0, v46
	v_max_f32_e32 v41, 0, v47
	v_max_f32_e32 v43, 0, v43
	s_mov_b32 s13, 0x120000
	v_pk_mul_f32 v[46:47], v[40:41], v[40:41]
	v_pk_mul_f32 v[52:53], v[42:43], v[42:43]
	v_cvt_pk_bf16_f32 v40, v44, v45
	v_add_co_u32_e32 v44, vcc, s13, v134
	v_cvt_pk_bf16_f32 v41, v46, v47
	v_cvt_pk_bf16_f32 v42, v50, v51
	v_cvt_pk_bf16_f32 v43, v52, v53
	v_addc_co_u32_e32 v45, vcc, 0, v135, vcc
	v_max_f32_e32 v32, 0, v32
	v_max_f32_e32 v33, 0, v33
	global_store_dwordx4 v[44:45], v[40:43], off
	s_nop 1
	v_pk_mul_f32 v[40:41], v[32:33], v[32:33]
	v_max_f32_e32 v34, 0, v34
	v_max_f32_e32 v36, 0, v36
	v_max_f32_e32 v37, 0, v37
	v_max_f32_e32 v32, 0, v38
	v_max_f32_e32 v33, 0, v39
	v_max_f32_e32 v35, 0, v35
	s_mov_b64 s[26:27], 0x120000
	v_pk_mul_f32 v[36:37], v[36:37], v[36:37]
	v_pk_mul_f32 v[38:39], v[32:33], v[32:33]
	v_pk_mul_f32 v[42:43], v[34:35], v[34:35]
	v_lshl_add_u64 v[48:49], v[134:135], 0, s[26:27]
	v_cvt_pk_bf16_f32 v32, v36, v37
	v_cvt_pk_bf16_f32 v33, v38, v39
	v_cvt_pk_bf16_f32 v34, v40, v41
	v_cvt_pk_bf16_f32 v35, v42, v43
	v_max_f32_e32 v24, 0, v24
	v_max_f32_e32 v25, 0, v25
	global_store_dwordx4 v[48:49], v[32:35], off offset:256
	s_nop 1
	v_pk_mul_f32 v[34:35], v[24:25], v[24:25]
	v_max_f32_e32 v28, 0, v28
	v_max_f32_e32 v29, 0, v29
	v_max_f32_e32 v26, 0, v26
	v_pk_mul_f32 v[28:29], v[28:29], v[28:29]
	v_max_f32_e32 v24, 0, v30
	v_max_f32_e32 v25, 0, v31
	v_max_f32_e32 v27, 0, v27
	s_mov_b32 s13, 0x140000
	v_pk_mul_f32 v[30:31], v[24:25], v[24:25]
	v_pk_mul_f32 v[36:37], v[26:27], v[26:27]
	v_cvt_pk_bf16_f32 v24, v28, v29
	v_add_co_u32_e32 v28, vcc, s13, v134
	v_cvt_pk_bf16_f32 v25, v30, v31
	v_cvt_pk_bf16_f32 v26, v34, v35
	v_cvt_pk_bf16_f32 v27, v36, v37
	v_addc_co_u32_e32 v29, vcc, 0, v135, vcc
	v_max_f32_e32 v16, 0, v16
	v_max_f32_e32 v17, 0, v17
	global_store_dwordx4 v[28:29], v[24:27], off
	s_nop 1
	v_pk_mul_f32 v[24:25], v[16:17], v[16:17]
	v_max_f32_e32 v18, 0, v18
	v_max_f32_e32 v20, 0, v20
	v_max_f32_e32 v21, 0, v21
	v_max_f32_e32 v16, 0, v22
	v_max_f32_e32 v17, 0, v23
	v_max_f32_e32 v19, 0, v19
	s_mov_b64 s[26:27], 0x140000
	v_pk_mul_f32 v[20:21], v[20:21], v[20:21]
	v_pk_mul_f32 v[22:23], v[16:17], v[16:17]
	v_pk_mul_f32 v[26:27], v[18:19], v[18:19]
	v_lshl_add_u64 v[32:33], v[134:135], 0, s[26:27]
	v_cvt_pk_bf16_f32 v16, v20, v21
	v_cvt_pk_bf16_f32 v17, v22, v23
	v_cvt_pk_bf16_f32 v18, v24, v25
	v_cvt_pk_bf16_f32 v19, v26, v27
	v_max_f32_e32 v8, 0, v8
	v_max_f32_e32 v9, 0, v9
	global_store_dwordx4 v[32:33], v[16:19], off offset:256
	s_nop 1
	v_pk_mul_f32 v[18:19], v[8:9], v[8:9]
	v_max_f32_e32 v12, 0, v12
	v_max_f32_e32 v13, 0, v13
	v_max_f32_e32 v10, 0, v10
	v_pk_mul_f32 v[12:13], v[12:13], v[12:13]
	v_max_f32_e32 v8, 0, v14
	v_max_f32_e32 v9, 0, v15
	v_max_f32_e32 v11, 0, v11
	s_mov_b32 s13, 0x160000
	v_pk_mul_f32 v[14:15], v[8:9], v[8:9]
	v_pk_mul_f32 v[20:21], v[10:11], v[10:11]
	v_cvt_pk_bf16_f32 v8, v12, v13
	v_add_co_u32_e32 v12, vcc, s13, v134
	v_cvt_pk_bf16_f32 v9, v14, v15
	v_cvt_pk_bf16_f32 v10, v18, v19
	v_cvt_pk_bf16_f32 v11, v20, v21
	v_addc_co_u32_e32 v13, vcc, 0, v135, vcc
	v_max_f32_e32 v0, 0, v0
	v_max_f32_e32 v1, 0, v1
	global_store_dwordx4 v[12:13], v[8:11], off
	s_nop 1
	v_pk_mul_f32 v[8:9], v[0:1], v[0:1]
	v_max_f32_e32 v2, 0, v2
	v_max_f32_e32 v4, 0, v4
	v_max_f32_e32 v5, 0, v5
	v_max_f32_e32 v0, 0, v6
	v_max_f32_e32 v1, 0, v7
	v_max_f32_e32 v3, 0, v3
	s_mov_b64 s[26:27], 0x160000
	v_pk_mul_f32 v[4:5], v[4:5], v[4:5]
	v_pk_mul_f32 v[6:7], v[0:1], v[0:1]
	v_pk_mul_f32 v[10:11], v[2:3], v[2:3]
	v_lshl_add_u64 v[16:17], v[134:135], 0, s[26:27]
	v_cvt_pk_bf16_f32 v0, v4, v5
	v_cvt_pk_bf16_f32 v1, v6, v7
	v_cvt_pk_bf16_f32 v2, v8, v9
	v_cvt_pk_bf16_f32 v3, v10, v11
	s_andn2_b64 vcc, exec, s[8:9]
	s_mov_b64 s[8:9], -1
	global_store_dwordx4 v[16:17], v[0:3], off offset:256
	s_cbranch_vccnz .LBB0_795
	s_andn2_b64 vcc, exec, s[0:1]
	s_cbranch_vccnz .LBB0_794
	s_barrier
	s_branch .LBB0_794
